# All five GEMM instances: first K-loop iteration peeled with C=0 in each accumulator's first MFMA; per-unit 128-register zeroing removed
# baseline (speedup 1.0000x reference)
; #define PG8_STAGE(bufoff, gbase, voff) do { _Pragma("unroll") for (int _i = 0; _i < 2; ++_i) \
;         __builtin_amdgcn_global_load_lds((const unsigned*)((const char*)(gbase) + (voff)[_i]), (PG8_LAS unsigned*)(lds + (bufoff) + ldsw + _i * 8192), 16, 0, 0); } while (0)
; #define PG8_LDA(dst, b, h) do { _Pragma("unroll") for (int m = 0; m < 4; ++m) _Pragma("unroll") for (int k = 0; k < 2; ++k) dst[m][k] = *(const PG8_LAS bf16x8*)(lds + PG8_SA(b, h) + aoff + m * 2048 + k * 1024); } while (0)
; #define PG8_LDB(dst, b, h) do { _Pragma("unroll") for (int n = 0; n < 2; ++n) _Pragma("unroll") for (int k = 0; k < 2; ++k) dst[n][k] = *(const PG8_LAS bf16x8*)(lds + PG8_SB(b, h) + boff + n * 2048 + k * 1024); } while (0)
; #define PG8_MMA(ai, bj, At, Bt) do { __builtin_amdgcn_s_setprio(1); _Pragma("unroll") for (int m = 0; m < 4; ++m) _Pragma("unroll") for (int n = 0; n < 2; ++n) _Pragma("unroll") for (int k = 0; k < 2; ++k) \
;         acc[ai][bj][m][n] = __builtin_amdgcn_mfma_f32_16x16x32_bf16(Bt[n][k], At[m][k], acc[ai][bj][m][n], 0, 0, 0); __builtin_amdgcn_s_setprio(0); } while (0)
; #define PG8_WAIT_V(n) asm volatile("s_waitcnt vmcnt(" #n ")" ::: "memory")
; template <class Epi, class Sched, bool ALIGN_EPI = false, bool SP2 = false>
; __device__ __forceinline__ void gemm_phase(PG8_LAS unsigned char* lds, const Gemm g, const Sched& S, const Epi& E) {
;     ...
;         const char* nA = has_next ? (const char*)g.A + (size_t)nxt.pm * tstepA : cA; const char* nB = has_next ? (const char*)g.Bt + (size_t)nxt.pn * tstep : cB;
;         for (int t = 0; t < nt; t += 2) {
;             const bool last = (t == nt - 2);
;             const char* a1 = cA + (size_t)(t + 1) * kstep;
;             const char* a2 = last ? nA : cA + (size_t)(t + 2) * kstep; const char* b2 = last ? nB : cB + (size_t)(t + 2) * kstep;
;             const char* a3 = a2 + kstep; const char* b3 = b2 + kstep;
;             if (last && has_next) S.a_ready(nxt);
;             if constexpr (SP2) {
;             PG8_LDB(B0, 0, 0); PG8_LDB(B1, 0, 1); PG8_SCHED; PG8_LDA(At, 0, 0); PG8_STAGE(PG8_SA(1, 1), a1 + hstepA, voffA);
;             PG8_WAIT_V(8); PG8_WAIT_L(0); PG8_BAR; PG8_MMA(0, 0, At, B0); PG8_MMA(0, 1, At, B1); PG8_BAR; PG8_SCHED;
;             PG8_LDA(At, 0, 1); PG8_STAGE(PG8_SB(0, 0), b2, voffB); PG8_STAGE(PG8_SB(0, 1), b2 + hstep, voffB); PG8_STAGE(PG8_SA(0, 0), a2, voffA);
.LBB0_102:
	s_ashr_i32 s13, s12, 31
	s_lshl_b64 s[18:19], s[12:13], 19
	s_add_u32 s18, s30, s18
	s_addc_u32 s19, s31, s19
	s_and_b64 s[20:21], s[40:41], exec
	s_cselect_b32 s13, s19, s43
	s_cselect_b32 s51, s18, s42
	s_ashr_i32 s11, s10, 31
	s_lshl_b64 s[20:21], s[10:11], 19
	v_readlane_b32 s46, v254, 44
	v_readlane_b32 s47, v254, 45
	s_add_u32 s20, s46, s20
	s_addc_u32 s21, s47, s21
	s_and_b64 s[46:47], s[40:41], exec
	s_cselect_b32 s11, s21, s45
	s_cselect_b32 s52, s20, s44
	s_add_u32 s42, s42, 0x40080
	s_addc_u32 s43, s43, 0
	s_add_u32 s53, s44, 0x100
	s_addc_u32 s54, s45, 0
	s_mov_b32 s55, -2
	s_waitcnt vmcnt(0)
	s_add_u32 s44, s42, 0xfffc0080
	s_addc_u32 s45, s43, -1
	s_add_i32 s56, 0, 0x10000
	s_cmp_eq_u32 s55, 12
	s_cselect_b32 s47, s13, s45
	s_cselect_b32 s46, s51, s44
	v_add_u32_e32 v146, s56, v149
	s_cselect_b32 s45, s11, s54
	s_cselect_b32 s44, s52, s53
	s_add_i32 s58, 0, 0x14000
	ds_read_b128 v[158:161], v146
	ds_read_b128 v[162:165], v146 offset:1024
	ds_read_b128 v[166:169], v146 offset:2048
	ds_read_b128 v[170:173], v146 offset:3072
	v_add_u32_e32 v146, s58, v149
	ds_read_b128 v[174:177], v146
	ds_read_b128 v[178:181], v146 offset:1024
	ds_read_b128 v[182:185], v146 offset:2048
	ds_read_b128 v[186:189], v146 offset:3072
	v_lshl_add_u64 v[146:147], s[42:43], 0, v[142:143]
	s_add_i32 m0, s4, 0xc000
	ds_read_b128 v[190:193], v157
	ds_read_b128 v[198:201], v157 offset:1024
	ds_read_b128 v[202:205], v157 offset:2048
	ds_read_b128 v[206:209], v157 offset:3072
	ds_read_b128 v[210:213], v157 offset:4096
	ds_read_b128 v[214:217], v157 offset:5120
	ds_read_b128 v[218:221], v157 offset:6144
	ds_read_b128 v[222:225], v157 offset:7168
	global_load_lds_dwordx4 v[146:147], off
	v_lshl_add_u64 v[146:147], s[42:43], 0, v[144:145]
	s_add_i32 m0, s4, 0xe000
	s_nop 0
	global_load_lds_dwordx4 v[146:147], off
	s_waitcnt vmcnt(8)
	s_waitcnt lgkmcnt(0)
	s_barrier
	s_setprio 1
	s_waitcnt lgkmcnt(0)
	v_mfma_f32_16x16x32_bf16 v[132:135], v[158:161], v[190:193], 0
	v_mfma_f32_16x16x32_bf16 v[128:131], v[166:169], v[190:193], 0
	v_mfma_f32_16x16x32_bf16 v[120:123], v[158:161], v[202:205], 0
	v_mfma_f32_16x16x32_bf16 v[112:115], v[166:169], v[202:205], 0
	v_mfma_f32_16x16x32_bf16 v[104:107], v[158:161], v[210:213], 0
	v_mfma_f32_16x16x32_bf16 v[96:99], v[166:169], v[210:213], 0
	v_mfma_f32_16x16x32_bf16 v[88:91], v[158:161], v[218:221], 0
	v_mfma_f32_16x16x32_bf16 v[74:77], v[166:169], v[218:221], 0
	v_mfma_f32_16x16x32_bf16 v[132:135], v[162:165], v[198:201], v[132:135]
	v_mfma_f32_16x16x32_bf16 v[128:131], v[170:173], v[198:201], v[128:131]
	v_mfma_f32_16x16x32_bf16 v[120:123], v[162:165], v[206:209], v[120:123]
	v_mfma_f32_16x16x32_bf16 v[112:115], v[170:173], v[206:209], v[112:115]
	v_mfma_f32_16x16x32_bf16 v[104:107], v[162:165], v[214:217], v[104:107]
	v_mfma_f32_16x16x32_bf16 v[96:99], v[170:173], v[214:217], v[96:99]
	v_mfma_f32_16x16x32_bf16 v[88:91], v[162:165], v[222:225], v[88:91]
	v_mfma_f32_16x16x32_bf16 v[74:77], v[170:173], v[222:225], v[74:77]
	v_mfma_f32_16x16x32_bf16 v[124:127], v[174:177], v[190:193], 0
	v_mfma_f32_16x16x32_bf16 v[116:119], v[182:185], v[190:193], 0
	v_mfma_f32_16x16x32_bf16 v[108:111], v[174:177], v[202:205], 0
	v_mfma_f32_16x16x32_bf16 v[100:103], v[182:185], v[202:205], 0
	v_mfma_f32_16x16x32_bf16 v[92:95], v[174:177], v[210:213], 0
	v_mfma_f32_16x16x32_bf16 v[84:87], v[182:185], v[210:213], 0
	v_mfma_f32_16x16x32_bf16 v[70:73], v[174:177], v[218:221], 0
	v_mfma_f32_16x16x32_bf16 v[66:69], v[182:185], v[218:221], 0
	v_mfma_f32_16x16x32_bf16 v[124:127], v[178:181], v[198:201], v[124:127]
	v_mfma_f32_16x16x32_bf16 v[116:119], v[186:189], v[198:201], v[116:119]
	v_mfma_f32_16x16x32_bf16 v[108:111], v[178:181], v[206:209], v[108:111]
	v_mfma_f32_16x16x32_bf16 v[100:103], v[186:189], v[206:209], v[100:103]
	v_mfma_f32_16x16x32_bf16 v[92:95], v[178:181], v[214:217], v[92:95]
	v_mfma_f32_16x16x32_bf16 v[84:87], v[186:189], v[214:217], v[84:87]
	v_mfma_f32_16x16x32_bf16 v[70:73], v[178:181], v[222:225], v[70:73]
	v_mfma_f32_16x16x32_bf16 v[66:69], v[186:189], v[222:225], v[66:69]
	s_setprio 0
	s_barrier
	s_add_i32 s56, s56, s0
	v_lshl_add_u64 v[146:147], s[44:45], 0, v[138:139]
	s_mov_b32 m0, s56
	ds_read_b128 v[190:193], v157 offset:16384
	ds_read_b128 v[198:201], v157 offset:17408
	ds_read_b128 v[202:205], v157 offset:18432
	ds_read_b128 v[206:209], v157 offset:19456
	ds_read_b128 v[210:213], v157 offset:20480
	ds_read_b128 v[214:217], v157 offset:21504
	ds_read_b128 v[218:221], v157 offset:22528
	ds_read_b128 v[222:225], v157 offset:23552
	global_load_lds_dwordx4 v[146:147], off
	s_add_i32 m0, s56, 0x2000
	s_add_u32 s56, s44, 0x40000
	v_lshl_add_u64 v[150:151], s[44:45], 0, v[78:79]
	s_addc_u32 s57, s45, 0
	s_add_i32 s58, s58, s0
	global_load_lds_dwordx4 v[150:151], off
	v_lshl_add_u64 v[154:155], s[56:57], 0, v[138:139]
	s_mov_b32 m0, s58
	v_lshl_add_u64 v[194:195], s[46:47], 0, v[136:137]
	global_load_lds_dwordx4 v[154:155], off
	v_lshl_add_u64 v[154:155], s[56:57], 0, v[78:79]
	s_add_i32 m0, s58, 0x2000
	s_nop 0
	global_load_lds_dwordx4 v[154:155], off
	v_lshl_add_u64 v[154:155], s[46:47], 0, v[140:141]
	s_mov_b32 m0, s4
	s_nop 0
	global_load_lds_dwordx4 v[154:155], off
	s_mov_b32 m0, s5
	s_nop 0
	global_load_lds_dwordx4 v[194:195], off
	s_waitcnt vmcnt(8)
	s_waitcnt lgkmcnt(0)
	s_barrier
; #define PG8_STAGE(bufoff, gbase, voff) do { _Pragma("unroll") for (int _i = 0; _i < 2; ++_i) \
;         __builtin_amdgcn_global_load_lds((const unsigned*)((const char*)(gbase) + (voff)[_i]), (PG8_LAS unsigned*)(lds + (bufoff) + ldsw + _i * 8192), 16, 0, 0); } while (0)
; #define PG8_LDA(dst, b, h) do { _Pragma("unroll") for (int m = 0; m < 4; ++m) _Pragma("unroll") for (int k = 0; k < 2; ++k) dst[m][k] = *(const PG8_LAS bf16x8*)(lds + PG8_SA(b, h) + aoff + m * 2048 + k * 1024); } while (0)
; #define PG8_LDB(dst, b, h) do { _Pragma("unroll") for (int n = 0; n < 2; ++n) _Pragma("unroll") for (int k = 0; k < 2; ++k) dst[n][k] = *(const PG8_LAS bf16x8*)(lds + PG8_SB(b, h) + boff + n * 2048 + k * 1024); } while (0)
; #define PG8_MMA(ai, bj, At, Bt) do { __builtin_amdgcn_s_setprio(1); _Pragma("unroll") for (int m = 0; m < 4; ++m) _Pragma("unroll") for (int n = 0; n < 2; ++n) _Pragma("unroll") for (int k = 0; k < 2; ++k) \
;         acc[ai][bj][m][n] = __builtin_amdgcn_mfma_f32_16x16x32_bf16(Bt[n][k], At[m][k], acc[ai][bj][m][n], 0, 0, 0); __builtin_amdgcn_s_setprio(0); } while (0)
; #define PG8_WAIT_V(n) asm volatile("s_waitcnt vmcnt(" #n ")" ::: "memory")
; #define PG8_WAIT_L(n) asm volatile("s_waitcnt lgkmcnt(" #n ")" ::: "memory")
; #define PG8_BAR __builtin_amdgcn_s_barrier()
; #define PG8_SCHED __builtin_amdgcn_sched_barrier(0)
; template <class Epi, class Sched, bool ALIGN_EPI = false, bool SP2 = false>
; __device__ __forceinline__ void gemm_phase(PG8_LAS unsigned char* lds, const Gemm g, const Sched& S, const Epi& E) {
;     ...
;             PG8_WAIT_V(8); PG8_WAIT_L(0); PG8_BAR; PG8_MMA(1, 0, At, B0); PG8_MMA(1, 1, At, B1); PG8_BAR; PG8_SCHED;
;             PG8_LDB(B0, 1, 0); PG8_LDB(B1, 1, 1); PG8_SCHED; PG8_LDA(At, 1, 0); PG8_STAGE(PG8_SA(0, 1), a2 + hstepA, voffA);
;             PG8_WAIT_V(8); PG8_WAIT_L(0); PG8_BAR; PG8_MMA(0, 0, At, B0); PG8_MMA(0, 1, At, B1); PG8_BAR; PG8_SCHED;
	s_setprio 1
	s_waitcnt lgkmcnt(0)
	v_mfma_f32_16x16x32_bf16 v[62:65], v[158:161], v[190:193], 0
	v_mfma_f32_16x16x32_bf16 v[58:61], v[166:169], v[190:193], 0
	v_mfma_f32_16x16x32_bf16 v[50:53], v[158:161], v[202:205], 0
	v_mfma_f32_16x16x32_bf16 v[42:45], v[166:169], v[202:205], 0
	v_mfma_f32_16x16x32_bf16 v[34:37], v[158:161], v[210:213], 0
	v_mfma_f32_16x16x32_bf16 v[26:29], v[166:169], v[210:213], 0
	v_mfma_f32_16x16x32_bf16 v[18:21], v[158:161], v[218:221], 0
	v_mfma_f32_16x16x32_bf16 v[10:13], v[166:169], v[218:221], 0
	v_mfma_f32_16x16x32_bf16 v[62:65], v[162:165], v[198:201], v[62:65]
	v_mfma_f32_16x16x32_bf16 v[58:61], v[170:173], v[198:201], v[58:61]
	v_mfma_f32_16x16x32_bf16 v[50:53], v[162:165], v[206:209], v[50:53]
	v_mfma_f32_16x16x32_bf16 v[42:45], v[170:173], v[206:209], v[42:45]
	v_mfma_f32_16x16x32_bf16 v[34:37], v[162:165], v[214:217], v[34:37]
	v_mfma_f32_16x16x32_bf16 v[26:29], v[170:173], v[214:217], v[26:29]
	v_mfma_f32_16x16x32_bf16 v[18:21], v[162:165], v[222:225], v[18:21]
	v_mfma_f32_16x16x32_bf16 v[10:13], v[170:173], v[222:225], v[10:13]
	v_mfma_f32_16x16x32_bf16 v[54:57], v[174:177], v[190:193], 0
	v_mfma_f32_16x16x32_bf16 v[46:49], v[182:185], v[190:193], 0
	v_mfma_f32_16x16x32_bf16 v[38:41], v[174:177], v[202:205], 0
	v_mfma_f32_16x16x32_bf16 v[30:33], v[182:185], v[202:205], 0
	v_mfma_f32_16x16x32_bf16 v[22:25], v[174:177], v[210:213], 0
	v_mfma_f32_16x16x32_bf16 v[14:17], v[182:185], v[210:213], 0
	v_mfma_f32_16x16x32_bf16 v[6:9], v[174:177], v[218:221], 0
	v_mfma_f32_16x16x32_bf16 v[2:5], v[182:185], v[218:221], 0
	v_mfma_f32_16x16x32_bf16 v[54:57], v[178:181], v[198:201], v[54:57]
	v_mfma_f32_16x16x32_bf16 v[46:49], v[186:189], v[198:201], v[46:49]
	v_mfma_f32_16x16x32_bf16 v[38:41], v[178:181], v[206:209], v[38:41]
	v_mfma_f32_16x16x32_bf16 v[30:33], v[186:189], v[206:209], v[30:33]
	v_mfma_f32_16x16x32_bf16 v[22:25], v[178:181], v[214:217], v[22:25]
	v_mfma_f32_16x16x32_bf16 v[14:17], v[186:189], v[214:217], v[14:17]
	v_mfma_f32_16x16x32_bf16 v[6:9], v[178:181], v[222:225], v[6:9]
	v_mfma_f32_16x16x32_bf16 v[2:5], v[186:189], v[222:225], v[2:5]
	s_setprio 0
	s_barrier
	s_add_i32 s56, 0, 0x18000
	v_add_u32_e32 v148, s56, v149
	s_add_i32 s57, 0, 0x1c000
	ds_read_b128 v[158:161], v148
	ds_read_b128 v[162:165], v148 offset:1024
	ds_read_b128 v[166:169], v148 offset:2048
	ds_read_b128 v[170:173], v148 offset:3072
	v_add_u32_e32 v148, s57, v149
	ds_read_b128 v[174:177], v148
	ds_read_b128 v[178:181], v148 offset:1024
	ds_read_b128 v[182:185], v148 offset:2048
	ds_read_b128 v[186:189], v148 offset:3072
	s_add_u32 s46, s46, 0x40000
	s_addc_u32 s47, s47, 0
	s_mov_b32 m0, s16
	v_lshl_add_u64 v[226:227], s[46:47], 0, v[140:141]
	ds_read_b128 v[190:193], v157 offset:32768
	ds_read_b128 v[198:201], v157 offset:33792
	ds_read_b128 v[202:205], v157 offset:34816
	ds_read_b128 v[206:209], v157 offset:35840
	ds_read_b128 v[210:213], v157 offset:36864
	ds_read_b128 v[214:217], v157 offset:37888
	ds_read_b128 v[218:221], v157 offset:38912
	ds_read_b128 v[222:225], v157 offset:39936
	global_load_lds_dwordx4 v[226:227], off
	v_lshl_add_u64 v[226:227], s[46:47], 0, v[136:137]
	s_mov_b32 m0, s17
	s_nop 0
	global_load_lds_dwordx4 v[226:227], off
	s_waitcnt vmcnt(8)
	s_waitcnt lgkmcnt(0)
	s_barrier
	s_setprio 1
	s_waitcnt lgkmcnt(0)
	v_mfma_f32_16x16x32_bf16 v[132:135], v[158:161], v[190:193], v[132:135]
	v_mfma_f32_16x16x32_bf16 v[128:131], v[166:169], v[190:193], v[128:131]
	v_mfma_f32_16x16x32_bf16 v[120:123], v[158:161], v[202:205], v[120:123]
	v_mfma_f32_16x16x32_bf16 v[112:115], v[166:169], v[202:205], v[112:115]
	v_mfma_f32_16x16x32_bf16 v[104:107], v[158:161], v[210:213], v[104:107]
	v_mfma_f32_16x16x32_bf16 v[96:99], v[166:169], v[210:213], v[96:99]
	v_mfma_f32_16x16x32_bf16 v[88:91], v[158:161], v[218:221], v[88:91]
	v_mfma_f32_16x16x32_bf16 v[74:77], v[166:169], v[218:221], v[74:77]
	v_mfma_f32_16x16x32_bf16 v[132:135], v[162:165], v[198:201], v[132:135]
	v_mfma_f32_16x16x32_bf16 v[128:131], v[170:173], v[198:201], v[128:131]
	v_mfma_f32_16x16x32_bf16 v[120:123], v[162:165], v[206:209], v[120:123]
	v_mfma_f32_16x16x32_bf16 v[112:115], v[170:173], v[206:209], v[112:115]
	v_mfma_f32_16x16x32_bf16 v[104:107], v[162:165], v[214:217], v[104:107]
	v_mfma_f32_16x16x32_bf16 v[96:99], v[170:173], v[214:217], v[96:99]
	v_mfma_f32_16x16x32_bf16 v[88:91], v[162:165], v[222:225], v[88:91]
	v_mfma_f32_16x16x32_bf16 v[74:77], v[170:173], v[222:225], v[74:77]
	v_mfma_f32_16x16x32_bf16 v[124:127], v[174:177], v[190:193], v[124:127]
	v_mfma_f32_16x16x32_bf16 v[116:119], v[182:185], v[190:193], v[116:119]
	v_mfma_f32_16x16x32_bf16 v[108:111], v[174:177], v[202:205], v[108:111]
	v_mfma_f32_16x16x32_bf16 v[100:103], v[182:185], v[202:205], v[100:103]
	v_mfma_f32_16x16x32_bf16 v[92:95], v[174:177], v[210:213], v[92:95]
	v_mfma_f32_16x16x32_bf16 v[84:87], v[182:185], v[210:213], v[84:87]
	v_mfma_f32_16x16x32_bf16 v[70:73], v[174:177], v[218:221], v[70:73]
	v_mfma_f32_16x16x32_bf16 v[66:69], v[182:185], v[218:221], v[66:69]
	v_mfma_f32_16x16x32_bf16 v[124:127], v[178:181], v[198:201], v[124:127]
	v_mfma_f32_16x16x32_bf16 v[116:119], v[186:189], v[198:201], v[116:119]
	v_mfma_f32_16x16x32_bf16 v[108:111], v[178:181], v[206:209], v[108:111]
	v_mfma_f32_16x16x32_bf16 v[100:103], v[186:189], v[206:209], v[100:103]
	v_mfma_f32_16x16x32_bf16 v[92:95], v[178:181], v[214:217], v[92:95]
	v_mfma_f32_16x16x32_bf16 v[84:87], v[186:189], v[214:217], v[84:87]
	v_mfma_f32_16x16x32_bf16 v[70:73], v[178:181], v[222:225], v[70:73]
	v_mfma_f32_16x16x32_bf16 v[66:69], v[186:189], v[222:225], v[66:69]
	s_setprio 0
	s_barrier
; #define PG8_STAGE(bufoff, gbase, voff) do { _Pragma("unroll") for (int _i = 0; _i < 2; ++_i) \
;         __builtin_amdgcn_global_load_lds((const unsigned*)((const char*)(gbase) + (voff)[_i]), (PG8_LAS unsigned*)(lds + (bufoff) + ldsw + _i * 8192), 16, 0, 0); } while (0)
; #define PG8_LDA(dst, b, h) do { _Pragma("unroll") for (int m = 0; m < 4; ++m) _Pragma("unroll") for (int k = 0; k < 2; ++k) dst[m][k] = *(const PG8_LAS bf16x8*)(lds + PG8_SA(b, h) + aoff + m * 2048 + k * 1024); } while (0)
; #define PG8_MMA(ai, bj, At, Bt) do { __builtin_amdgcn_s_setprio(1); _Pragma("unroll") for (int m = 0; m < 4; ++m) _Pragma("unroll") for (int n = 0; n < 2; ++n) _Pragma("unroll") for (int k = 0; k < 2; ++k) \
;         acc[ai][bj][m][n] = __builtin_amdgcn_mfma_f32_16x16x32_bf16(Bt[n][k], At[m][k], acc[ai][bj][m][n], 0, 0, 0); __builtin_amdgcn_s_setprio(0); } while (0)
; #define PG8_WAIT_V(n) asm volatile("s_waitcnt vmcnt(" #n ")" ::: "memory")
; #define PG8_WAIT_L(n) asm volatile("s_waitcnt lgkmcnt(" #n ")" ::: "memory")
; #define PG8_BAR __builtin_amdgcn_s_barrier()
; #define PG8_SCHED __builtin_amdgcn_sched_barrier(0)
; template <class Epi, class Sched, bool ALIGN_EPI = false, bool SP2 = false>
; __device__ __forceinline__ void gemm_phase(PG8_LAS unsigned char* lds, const Gemm g, const Sched& S, const Epi& E) {
;     ...
;         for (int t = 0; t < nt; t += 2) {
;     ...
;             PG8_LDA(At, 1, 1); PG8_STAGE(PG8_SB(1, 0), b3, voffB); PG8_STAGE(PG8_SB(1, 1), b3 + hstep, voffB); PG8_STAGE(PG8_SA(1, 0), a3, voffA);
;             PG8_WAIT_V(8); PG8_WAIT_L(0); PG8_BAR; PG8_MMA(1, 0, At, B0); PG8_MMA(1, 1, At, B1); PG8_BAR; PG8_SCHED;
	s_add_i32 s46, s56, s0
	v_lshl_add_u64 v[146:147], v[146:147], 0, s[26:27]
	s_mov_b32 m0, s46
	ds_read_b128 v[190:193], v157 offset:49152
	ds_read_b128 v[198:201], v157 offset:50176
	ds_read_b128 v[202:205], v157 offset:51200
	ds_read_b128 v[206:209], v157 offset:52224
	ds_read_b128 v[210:213], v157 offset:53248
	ds_read_b128 v[214:217], v157 offset:54272
	ds_read_b128 v[218:221], v157 offset:55296
	ds_read_b128 v[222:225], v157 offset:56320
	global_load_lds_dwordx4 v[146:147], off
	s_add_i32 m0, s46, 0x2000
	s_add_u32 s44, s44, 0x40080
	v_lshl_add_u64 v[146:147], v[150:151], 0, s[26:27]
	s_addc_u32 s45, s45, 0
	s_add_i32 s46, s57, s0
	global_load_lds_dwordx4 v[146:147], off
	v_lshl_add_u64 v[146:147], s[44:45], 0, v[138:139]
	s_mov_b32 m0, s46
	s_nop 0
	global_load_lds_dwordx4 v[146:147], off
	v_lshl_add_u64 v[146:147], s[44:45], 0, v[78:79]
	s_add_i32 m0, s46, 0x2000
	s_nop 0
	global_load_lds_dwordx4 v[146:147], off
	v_lshl_add_u64 v[146:147], v[154:155], 0, s[26:27]
	s_mov_b32 m0, s24
	s_nop 0
	global_load_lds_dwordx4 v[146:147], off
	v_lshl_add_u64 v[146:147], v[194:195], 0, s[26:27]
	s_mov_b32 m0, s25
	s_nop 0
	global_load_lds_dwordx4 v[146:147], off
	s_waitcnt vmcnt(8)
	s_waitcnt lgkmcnt(0)
	s_barrier
	s_setprio 1
	s_waitcnt lgkmcnt(0)
	v_mfma_f32_16x16x32_bf16 v[62:65], v[158:161], v[190:193], v[62:65]
	v_mfma_f32_16x16x32_bf16 v[58:61], v[166:169], v[190:193], v[58:61]
	v_mfma_f32_16x16x32_bf16 v[50:53], v[158:161], v[202:205], v[50:53]
	v_mfma_f32_16x16x32_bf16 v[42:45], v[166:169], v[202:205], v[42:45]
	v_mfma_f32_16x16x32_bf16 v[34:37], v[158:161], v[210:213], v[34:37]
	v_mfma_f32_16x16x32_bf16 v[26:29], v[166:169], v[210:213], v[26:29]
	v_mfma_f32_16x16x32_bf16 v[18:21], v[158:161], v[218:221], v[18:21]
	v_mfma_f32_16x16x32_bf16 v[10:13], v[166:169], v[218:221], v[10:13]
	v_mfma_f32_16x16x32_bf16 v[62:65], v[162:165], v[198:201], v[62:65]
	v_mfma_f32_16x16x32_bf16 v[58:61], v[170:173], v[198:201], v[58:61]
	v_mfma_f32_16x16x32_bf16 v[50:53], v[162:165], v[206:209], v[50:53]
	v_mfma_f32_16x16x32_bf16 v[42:45], v[170:173], v[206:209], v[42:45]
	v_mfma_f32_16x16x32_bf16 v[34:37], v[162:165], v[214:217], v[34:37]
	v_mfma_f32_16x16x32_bf16 v[26:29], v[170:173], v[214:217], v[26:29]
	v_mfma_f32_16x16x32_bf16 v[18:21], v[162:165], v[222:225], v[18:21]
	v_mfma_f32_16x16x32_bf16 v[10:13], v[170:173], v[222:225], v[10:13]
	v_mfma_f32_16x16x32_bf16 v[54:57], v[174:177], v[190:193], v[54:57]
	v_mfma_f32_16x16x32_bf16 v[46:49], v[182:185], v[190:193], v[46:49]
	v_mfma_f32_16x16x32_bf16 v[38:41], v[174:177], v[202:205], v[38:41]
	v_mfma_f32_16x16x32_bf16 v[30:33], v[182:185], v[202:205], v[30:33]
	v_mfma_f32_16x16x32_bf16 v[22:25], v[174:177], v[210:213], v[22:25]
	v_mfma_f32_16x16x32_bf16 v[14:17], v[182:185], v[210:213], v[14:17]
	v_mfma_f32_16x16x32_bf16 v[6:9], v[174:177], v[218:221], v[6:9]
	v_mfma_f32_16x16x32_bf16 v[2:5], v[182:185], v[218:221], v[2:5]
	v_mfma_f32_16x16x32_bf16 v[54:57], v[178:181], v[198:201], v[54:57]
	v_mfma_f32_16x16x32_bf16 v[46:49], v[186:189], v[198:201], v[46:49]
	v_mfma_f32_16x16x32_bf16 v[38:41], v[178:181], v[206:209], v[38:41]
	v_mfma_f32_16x16x32_bf16 v[30:33], v[186:189], v[206:209], v[30:33]
	v_mfma_f32_16x16x32_bf16 v[22:25], v[178:181], v[214:217], v[22:25]
	v_mfma_f32_16x16x32_bf16 v[14:17], v[186:189], v[214:217], v[14:17]
	v_mfma_f32_16x16x32_bf16 v[6:9], v[178:181], v[222:225], v[6:9]
	v_mfma_f32_16x16x32_bf16 v[2:5], v[186:189], v[222:225], v[2:5]
	s_setprio 0
	s_barrier
	s_add_i32 s55, s55, 2
	s_add_u32 s42, s42, 0x100
	s_addc_u32 s43, s43, 0
	s_add_u32 s53, s53, 0x100
	s_addc_u32 s54, s54, 0
	s_cmp_gt_u32 s55, 13

; #define PG8_STAGE(bufoff, gbase, voff) do { _Pragma("unroll") for (int _i = 0; _i < 2; ++_i) \
;         __builtin_amdgcn_global_load_lds((const unsigned*)((const char*)(gbase) + (voff)[_i]), (PG8_LAS unsigned*)(lds + (bufoff) + ldsw + _i * 8192), 16, 0, 0); } while (0)
; #define PG8_LDA(dst, b, h) do { _Pragma("unroll") for (int m = 0; m < 4; ++m) _Pragma("unroll") for (int k = 0; k < 2; ++k) dst[m][k] = *(const PG8_LAS bf16x8*)(lds + PG8_SA(b, h) + aoff + m * 2048 + k * 1024); } while (0)
; #define PG8_LDB(dst, b, h) do { _Pragma("unroll") for (int n = 0; n < 2; ++n) _Pragma("unroll") for (int k = 0; k < 2; ++k) dst[n][k] = *(const PG8_LAS bf16x8*)(lds + PG8_SB(b, h) + boff + n * 2048 + k * 1024); } while (0)
; #define PG8_MMA(ai, bj, At, Bt) do { __builtin_amdgcn_s_setprio(1); _Pragma("unroll") for (int m = 0; m < 4; ++m) _Pragma("unroll") for (int n = 0; n < 2; ++n) _Pragma("unroll") for (int k = 0; k < 2; ++k) \
;         acc[ai][bj][m][n] = __builtin_amdgcn_mfma_f32_16x16x32_bf16(Bt[n][k], At[m][k], acc[ai][bj][m][n], 0, 0, 0); __builtin_amdgcn_s_setprio(0); } while (0)
; #define PG8_WAIT_V(n) asm volatile("s_waitcnt vmcnt(" #n ")" ::: "memory")
; template <class Epi, class Sched, bool ALIGN_EPI = false, bool SP2 = false>
; __device__ __forceinline__ void gemm_phase(PG8_LAS unsigned char* lds, const Gemm g, const Sched& S, const Epi& E) {
;     ...
;         const char* nA = has_next ? (const char*)g.A + (size_t)nxt.pm * tstepA : cA; const char* nB = has_next ? (const char*)g.Bt + (size_t)nxt.pn * tstep : cB;
;         for (int t = 0; t < nt; t += 2) {
;             const bool last = (t == nt - 2);
;             const char* a1 = cA + (size_t)(t + 1) * kstep;
;             const char* a2 = last ? nA : cA + (size_t)(t + 2) * kstep; const char* b2 = last ? nB : cB + (size_t)(t + 2) * kstep;
;             const char* a3 = a2 + kstep; const char* b3 = b2 + kstep;
;             if (last && has_next) S.a_ready(nxt);
;             if constexpr (SP2) {
;             PG8_LDB(B0, 0, 0); PG8_LDB(B1, 0, 1); PG8_SCHED; PG8_LDA(At, 0, 0); PG8_STAGE(PG8_SA(1, 1), a1 + hstepA, voffA);
;             PG8_WAIT_V(8); PG8_WAIT_L(0); PG8_BAR; PG8_MMA(0, 0, At, B0); PG8_MMA(0, 1, At, B1); PG8_BAR; PG8_SCHED;
;             PG8_LDA(At, 0, 1); PG8_STAGE(PG8_SB(0, 0), b2, voffB); PG8_STAGE(PG8_SB(0, 1), b2 + hstep, voffB); PG8_STAGE(PG8_SA(0, 0), a2, voffA);
.LBB0_369:
	s_ashr_i32 s19, s18, 31
	s_lshl_b64 s[20:21], s[18:19], 19
	s_add_u32 s20, s30, s20
	s_addc_u32 s21, s31, s21
	s_and_b64 s[42:43], s[40:41], exec
	s_cselect_b32 s19, s21, s45
	s_cselect_b32 s52, s20, s44
	s_ashr_i32 s13, s12, 31
	s_lshl_b64 s[42:43], s[12:13], 19
	v_readlane_b32 s48, v254, 48
	v_readlane_b32 s49, v254, 49
	s_add_u32 s42, s48, s42
	s_addc_u32 s43, s49, s43
	s_and_b64 s[48:49], s[40:41], exec
	s_cselect_b32 s13, s43, s47
	s_cselect_b32 s53, s42, s46
	s_add_u32 s44, s44, 0x40080
	s_addc_u32 s45, s45, 0
	s_add_u32 s54, s46, 0x100
	s_addc_u32 s55, s47, 0
	s_mov_b32 s56, -2
	s_waitcnt vmcnt(0)
	s_add_u32 s46, s44, 0xfffc0080
	s_addc_u32 s47, s45, -1
	s_add_i32 s57, 0, 0x10000
	s_cmp_eq_u32 s56, 12
	s_cselect_b32 s49, s19, s47
	s_cselect_b32 s48, s52, s46
	v_add_u32_e32 v148, s57, v151
	s_cselect_b32 s47, s13, s55
	s_cselect_b32 s46, s53, s54
	s_waitcnt lgkmcnt(0)
	s_add_i32 s60, 0, 0x14000
	ds_read_b128 v[160:163], v148
	ds_read_b128 v[164:167], v148 offset:1024
	ds_read_b128 v[168:171], v148 offset:2048
	ds_read_b128 v[172:175], v148 offset:3072
	v_add_u32_e32 v148, s60, v151
	ds_read_b128 v[176:179], v148
	ds_read_b128 v[180:183], v148 offset:1024
	ds_read_b128 v[184:187], v148 offset:2048
	ds_read_b128 v[188:191], v148 offset:3072
	v_lshl_add_u64 v[148:149], s[44:45], 0, v[144:145]
	s_add_i32 m0, s4, 0xc000
	ds_read_b128 v[192:195], v159
	ds_read_b128 v[198:201], v159 offset:1024
	ds_read_b128 v[202:205], v159 offset:2048
	ds_read_b128 v[206:209], v159 offset:3072
	ds_read_b128 v[210:213], v159 offset:4096
	ds_read_b128 v[214:217], v159 offset:5120
	ds_read_b128 v[218:221], v159 offset:6144
	ds_read_b128 v[222:225], v159 offset:7168
	global_load_lds_dwordx4 v[148:149], off
	v_lshl_add_u64 v[148:149], s[44:45], 0, v[146:147]
	s_add_i32 m0, s4, 0xe000
	s_nop 0
	global_load_lds_dwordx4 v[148:149], off
	s_waitcnt vmcnt(8)
	s_waitcnt lgkmcnt(0)
	s_barrier
	s_setprio 1
	s_waitcnt lgkmcnt(0)
	v_mfma_f32_16x16x32_bf16 v[132:135], v[160:163], v[192:195], 0
	v_mfma_f32_16x16x32_bf16 v[128:131], v[168:171], v[192:195], 0
	v_mfma_f32_16x16x32_bf16 v[120:123], v[160:163], v[202:205], 0
	v_mfma_f32_16x16x32_bf16 v[112:115], v[168:171], v[202:205], 0
	v_mfma_f32_16x16x32_bf16 v[104:107], v[160:163], v[210:213], 0
	v_mfma_f32_16x16x32_bf16 v[96:99], v[168:171], v[210:213], 0
	v_mfma_f32_16x16x32_bf16 v[88:91], v[160:163], v[218:221], 0
	v_mfma_f32_16x16x32_bf16 v[74:77], v[168:171], v[218:221], 0
	v_mfma_f32_16x16x32_bf16 v[132:135], v[164:167], v[198:201], v[132:135]
	v_mfma_f32_16x16x32_bf16 v[128:131], v[172:175], v[198:201], v[128:131]
	v_mfma_f32_16x16x32_bf16 v[120:123], v[164:167], v[206:209], v[120:123]
	v_mfma_f32_16x16x32_bf16 v[112:115], v[172:175], v[206:209], v[112:115]
	v_mfma_f32_16x16x32_bf16 v[104:107], v[164:167], v[214:217], v[104:107]
	v_mfma_f32_16x16x32_bf16 v[96:99], v[172:175], v[214:217], v[96:99]
	v_mfma_f32_16x16x32_bf16 v[88:91], v[164:167], v[222:225], v[88:91]
	v_mfma_f32_16x16x32_bf16 v[74:77], v[172:175], v[222:225], v[74:77]
	v_mfma_f32_16x16x32_bf16 v[124:127], v[176:179], v[192:195], 0
	v_mfma_f32_16x16x32_bf16 v[116:119], v[184:187], v[192:195], 0
	v_mfma_f32_16x16x32_bf16 v[108:111], v[176:179], v[202:205], 0
	v_mfma_f32_16x16x32_bf16 v[100:103], v[184:187], v[202:205], 0
	v_mfma_f32_16x16x32_bf16 v[92:95], v[176:179], v[210:213], 0
	v_mfma_f32_16x16x32_bf16 v[84:87], v[184:187], v[210:213], 0
	v_mfma_f32_16x16x32_bf16 v[70:73], v[176:179], v[218:221], 0
	v_mfma_f32_16x16x32_bf16 v[66:69], v[184:187], v[218:221], 0
	v_mfma_f32_16x16x32_bf16 v[124:127], v[180:183], v[198:201], v[124:127]
	v_mfma_f32_16x16x32_bf16 v[116:119], v[188:191], v[198:201], v[116:119]
	v_mfma_f32_16x16x32_bf16 v[108:111], v[180:183], v[206:209], v[108:111]
	v_mfma_f32_16x16x32_bf16 v[100:103], v[188:191], v[206:209], v[100:103]
	v_mfma_f32_16x16x32_bf16 v[92:95], v[180:183], v[214:217], v[92:95]
	v_mfma_f32_16x16x32_bf16 v[84:87], v[188:191], v[214:217], v[84:87]
	v_mfma_f32_16x16x32_bf16 v[70:73], v[180:183], v[222:225], v[70:73]
	v_mfma_f32_16x16x32_bf16 v[66:69], v[188:191], v[222:225], v[66:69]
	s_setprio 0
	s_barrier
	s_add_i32 s57, s57, s0
	v_lshl_add_u64 v[148:149], s[46:47], 0, v[138:139]
	s_mov_b32 m0, s57
	ds_read_b128 v[192:195], v159 offset:16384
	ds_read_b128 v[198:201], v159 offset:17408
	ds_read_b128 v[202:205], v159 offset:18432
	ds_read_b128 v[206:209], v159 offset:19456
	ds_read_b128 v[210:213], v159 offset:20480
	ds_read_b128 v[214:217], v159 offset:21504
	ds_read_b128 v[218:221], v159 offset:22528
	ds_read_b128 v[222:225], v159 offset:23552
	global_load_lds_dwordx4 v[148:149], off
	s_add_i32 m0, s57, 0x2000
	s_add_u32 s58, s46, 0x40000
	v_lshl_add_u64 v[152:153], s[46:47], 0, v[78:79]
	s_addc_u32 s59, s47, 0
	s_add_i32 s57, s60, s0
	global_load_lds_dwordx4 v[152:153], off
	v_lshl_add_u64 v[156:157], s[58:59], 0, v[138:139]
	s_mov_b32 m0, s57
	v_lshl_add_u64 v[226:227], s[48:49], 0, v[136:137]
	global_load_lds_dwordx4 v[156:157], off
	v_lshl_add_u64 v[156:157], s[58:59], 0, v[78:79]
	s_add_i32 m0, s57, 0x2000
	s_nop 0
	global_load_lds_dwordx4 v[156:157], off
	v_lshl_add_u64 v[156:157], s[48:49], 0, v[140:141]
	s_mov_b32 m0, s4
	s_nop 0
	global_load_lds_dwordx4 v[156:157], off
	s_mov_b32 m0, s5
	s_nop 0
	global_load_lds_dwordx4 v[226:227], off
	s_waitcnt vmcnt(8)
	s_waitcnt lgkmcnt(0)
	s_barrier
; #define PG8_STAGE(bufoff, gbase, voff) do { _Pragma("unroll") for (int _i = 0; _i < 2; ++_i) \
;         __builtin_amdgcn_global_load_lds((const unsigned*)((const char*)(gbase) + (voff)[_i]), (PG8_LAS unsigned*)(lds + (bufoff) + ldsw + _i * 8192), 16, 0, 0); } while (0)
; #define PG8_LDA(dst, b, h) do { _Pragma("unroll") for (int m = 0; m < 4; ++m) _Pragma("unroll") for (int k = 0; k < 2; ++k) dst[m][k] = *(const PG8_LAS bf16x8*)(lds + PG8_SA(b, h) + aoff + m * 2048 + k * 1024); } while (0)
; #define PG8_LDB(dst, b, h) do { _Pragma("unroll") for (int n = 0; n < 2; ++n) _Pragma("unroll") for (int k = 0; k < 2; ++k) dst[n][k] = *(const PG8_LAS bf16x8*)(lds + PG8_SB(b, h) + boff + n * 2048 + k * 1024); } while (0)
; #define PG8_MMA(ai, bj, At, Bt) do { __builtin_amdgcn_s_setprio(1); _Pragma("unroll") for (int m = 0; m < 4; ++m) _Pragma("unroll") for (int n = 0; n < 2; ++n) _Pragma("unroll") for (int k = 0; k < 2; ++k) \
;         acc[ai][bj][m][n] = __builtin_amdgcn_mfma_f32_16x16x32_bf16(Bt[n][k], At[m][k], acc[ai][bj][m][n], 0, 0, 0); __builtin_amdgcn_s_setprio(0); } while (0)
; #define PG8_WAIT_V(n) asm volatile("s_waitcnt vmcnt(" #n ")" ::: "memory")
; #define PG8_WAIT_L(n) asm volatile("s_waitcnt lgkmcnt(" #n ")" ::: "memory")
; #define PG8_BAR __builtin_amdgcn_s_barrier()
; #define PG8_SCHED __builtin_amdgcn_sched_barrier(0)
; template <class Epi, class Sched, bool ALIGN_EPI = false, bool SP2 = false>
; __device__ __forceinline__ void gemm_phase(PG8_LAS unsigned char* lds, const Gemm g, const Sched& S, const Epi& E) {
;     ...
;             PG8_WAIT_V(8); PG8_WAIT_L(0); PG8_BAR; PG8_MMA(1, 0, At, B0); PG8_MMA(1, 1, At, B1); PG8_BAR; PG8_SCHED;
;             PG8_LDB(B0, 1, 0); PG8_LDB(B1, 1, 1); PG8_SCHED; PG8_LDA(At, 1, 0); PG8_STAGE(PG8_SA(0, 1), a2 + hstepA, voffA);
;             PG8_WAIT_V(8); PG8_WAIT_L(0); PG8_BAR; PG8_MMA(0, 0, At, B0); PG8_MMA(0, 1, At, B1); PG8_BAR; PG8_SCHED;
	s_setprio 1
	s_waitcnt lgkmcnt(0)
	v_mfma_f32_16x16x32_bf16 v[62:65], v[160:163], v[192:195], 0
	v_mfma_f32_16x16x32_bf16 v[58:61], v[168:171], v[192:195], 0
	v_mfma_f32_16x16x32_bf16 v[50:53], v[160:163], v[202:205], 0
	v_mfma_f32_16x16x32_bf16 v[42:45], v[168:171], v[202:205], 0
	v_mfma_f32_16x16x32_bf16 v[34:37], v[160:163], v[210:213], 0
	v_mfma_f32_16x16x32_bf16 v[26:29], v[168:171], v[210:213], 0
	v_mfma_f32_16x16x32_bf16 v[18:21], v[160:163], v[218:221], 0
	v_mfma_f32_16x16x32_bf16 v[10:13], v[168:171], v[218:221], 0
	v_mfma_f32_16x16x32_bf16 v[62:65], v[164:167], v[198:201], v[62:65]
	v_mfma_f32_16x16x32_bf16 v[58:61], v[172:175], v[198:201], v[58:61]
	v_mfma_f32_16x16x32_bf16 v[50:53], v[164:167], v[206:209], v[50:53]
	v_mfma_f32_16x16x32_bf16 v[42:45], v[172:175], v[206:209], v[42:45]
	v_mfma_f32_16x16x32_bf16 v[34:37], v[164:167], v[214:217], v[34:37]
	v_mfma_f32_16x16x32_bf16 v[26:29], v[172:175], v[214:217], v[26:29]
	v_mfma_f32_16x16x32_bf16 v[18:21], v[164:167], v[222:225], v[18:21]
	v_mfma_f32_16x16x32_bf16 v[10:13], v[172:175], v[222:225], v[10:13]
	v_mfma_f32_16x16x32_bf16 v[54:57], v[176:179], v[192:195], 0
	v_mfma_f32_16x16x32_bf16 v[46:49], v[184:187], v[192:195], 0
	v_mfma_f32_16x16x32_bf16 v[38:41], v[176:179], v[202:205], 0
	v_mfma_f32_16x16x32_bf16 v[30:33], v[184:187], v[202:205], 0
	v_mfma_f32_16x16x32_bf16 v[22:25], v[176:179], v[210:213], 0
	v_mfma_f32_16x16x32_bf16 v[14:17], v[184:187], v[210:213], 0
	v_mfma_f32_16x16x32_bf16 v[6:9], v[176:179], v[218:221], 0
	v_mfma_f32_16x16x32_bf16 v[2:5], v[184:187], v[218:221], 0
	v_mfma_f32_16x16x32_bf16 v[54:57], v[180:183], v[198:201], v[54:57]
	v_mfma_f32_16x16x32_bf16 v[46:49], v[188:191], v[198:201], v[46:49]
	v_mfma_f32_16x16x32_bf16 v[38:41], v[180:183], v[206:209], v[38:41]
	v_mfma_f32_16x16x32_bf16 v[30:33], v[188:191], v[206:209], v[30:33]
	v_mfma_f32_16x16x32_bf16 v[22:25], v[180:183], v[214:217], v[22:25]
	v_mfma_f32_16x16x32_bf16 v[14:17], v[188:191], v[214:217], v[14:17]
	v_mfma_f32_16x16x32_bf16 v[6:9], v[180:183], v[222:225], v[6:9]
	v_mfma_f32_16x16x32_bf16 v[2:5], v[188:191], v[222:225], v[2:5]
	s_setprio 0
	s_barrier
	s_add_i32 s57, 0, 0x18000
	v_add_u32_e32 v150, s57, v151
	s_add_i32 s58, 0, 0x1c000
	ds_read_b128 v[160:163], v150
	ds_read_b128 v[164:167], v150 offset:1024
	ds_read_b128 v[168:171], v150 offset:2048
	ds_read_b128 v[172:175], v150 offset:3072
	v_add_u32_e32 v150, s58, v151
	ds_read_b128 v[176:179], v150
	ds_read_b128 v[180:183], v150 offset:1024
	ds_read_b128 v[184:187], v150 offset:2048
	ds_read_b128 v[188:191], v150 offset:3072
	s_add_u32 s48, s48, 0x40000
	s_addc_u32 s49, s49, 0
	s_mov_b32 m0, s16
	v_lshl_add_u64 v[236:237], s[48:49], 0, v[140:141]
	ds_read_b128 v[192:195], v159 offset:32768
	ds_read_b128 v[198:201], v159 offset:33792
	ds_read_b128 v[202:205], v159 offset:34816
	ds_read_b128 v[206:209], v159 offset:35840
	ds_read_b128 v[210:213], v159 offset:36864
	ds_read_b128 v[214:217], v159 offset:37888
	ds_read_b128 v[218:221], v159 offset:38912
	ds_read_b128 v[222:225], v159 offset:39936
	global_load_lds_dwordx4 v[236:237], off
	v_lshl_add_u64 v[236:237], s[48:49], 0, v[136:137]
	s_mov_b32 m0, s17
	s_nop 0
	global_load_lds_dwordx4 v[236:237], off
	s_waitcnt vmcnt(8)
	s_waitcnt lgkmcnt(0)
	s_barrier
	s_setprio 1
	s_waitcnt lgkmcnt(0)
	v_mfma_f32_16x16x32_bf16 v[132:135], v[160:163], v[192:195], v[132:135]
	v_mfma_f32_16x16x32_bf16 v[128:131], v[168:171], v[192:195], v[128:131]
	v_mfma_f32_16x16x32_bf16 v[120:123], v[160:163], v[202:205], v[120:123]
	v_mfma_f32_16x16x32_bf16 v[112:115], v[168:171], v[202:205], v[112:115]
	v_mfma_f32_16x16x32_bf16 v[104:107], v[160:163], v[210:213], v[104:107]
	v_mfma_f32_16x16x32_bf16 v[96:99], v[168:171], v[210:213], v[96:99]
	v_mfma_f32_16x16x32_bf16 v[88:91], v[160:163], v[218:221], v[88:91]
	v_mfma_f32_16x16x32_bf16 v[74:77], v[168:171], v[218:221], v[74:77]
	v_mfma_f32_16x16x32_bf16 v[132:135], v[164:167], v[198:201], v[132:135]
	v_mfma_f32_16x16x32_bf16 v[128:131], v[172:175], v[198:201], v[128:131]
	v_mfma_f32_16x16x32_bf16 v[120:123], v[164:167], v[206:209], v[120:123]
	v_mfma_f32_16x16x32_bf16 v[112:115], v[172:175], v[206:209], v[112:115]
	v_mfma_f32_16x16x32_bf16 v[104:107], v[164:167], v[214:217], v[104:107]
	v_mfma_f32_16x16x32_bf16 v[96:99], v[172:175], v[214:217], v[96:99]
	v_mfma_f32_16x16x32_bf16 v[88:91], v[164:167], v[222:225], v[88:91]
	v_mfma_f32_16x16x32_bf16 v[74:77], v[172:175], v[222:225], v[74:77]
	v_mfma_f32_16x16x32_bf16 v[124:127], v[176:179], v[192:195], v[124:127]
	v_mfma_f32_16x16x32_bf16 v[116:119], v[184:187], v[192:195], v[116:119]
	v_mfma_f32_16x16x32_bf16 v[108:111], v[176:179], v[202:205], v[108:111]
	v_mfma_f32_16x16x32_bf16 v[100:103], v[184:187], v[202:205], v[100:103]
	v_mfma_f32_16x16x32_bf16 v[92:95], v[176:179], v[210:213], v[92:95]
	v_mfma_f32_16x16x32_bf16 v[84:87], v[184:187], v[210:213], v[84:87]
	v_mfma_f32_16x16x32_bf16 v[70:73], v[176:179], v[218:221], v[70:73]
	v_mfma_f32_16x16x32_bf16 v[66:69], v[184:187], v[218:221], v[66:69]
	v_mfma_f32_16x16x32_bf16 v[124:127], v[180:183], v[198:201], v[124:127]
	v_mfma_f32_16x16x32_bf16 v[116:119], v[188:191], v[198:201], v[116:119]
	v_mfma_f32_16x16x32_bf16 v[108:111], v[180:183], v[206:209], v[108:111]
	v_mfma_f32_16x16x32_bf16 v[100:103], v[188:191], v[206:209], v[100:103]
	v_mfma_f32_16x16x32_bf16 v[92:95], v[180:183], v[214:217], v[92:95]
	v_mfma_f32_16x16x32_bf16 v[84:87], v[188:191], v[214:217], v[84:87]
	v_mfma_f32_16x16x32_bf16 v[70:73], v[180:183], v[222:225], v[70:73]
	v_mfma_f32_16x16x32_bf16 v[66:69], v[188:191], v[222:225], v[66:69]
	s_setprio 0
	s_barrier
; #define PG8_STAGE(bufoff, gbase, voff) do { _Pragma("unroll") for (int _i = 0; _i < 2; ++_i) \
;         __builtin_amdgcn_global_load_lds((const unsigned*)((const char*)(gbase) + (voff)[_i]), (PG8_LAS unsigned*)(lds + (bufoff) + ldsw + _i * 8192), 16, 0, 0); } while (0)
; #define PG8_LDA(dst, b, h) do { _Pragma("unroll") for (int m = 0; m < 4; ++m) _Pragma("unroll") for (int k = 0; k < 2; ++k) dst[m][k] = *(const PG8_LAS bf16x8*)(lds + PG8_SA(b, h) + aoff + m * 2048 + k * 1024); } while (0)
; #define PG8_MMA(ai, bj, At, Bt) do { __builtin_amdgcn_s_setprio(1); _Pragma("unroll") for (int m = 0; m < 4; ++m) _Pragma("unroll") for (int n = 0; n < 2; ++n) _Pragma("unroll") for (int k = 0; k < 2; ++k) \
;         acc[ai][bj][m][n] = __builtin_amdgcn_mfma_f32_16x16x32_bf16(Bt[n][k], At[m][k], acc[ai][bj][m][n], 0, 0, 0); __builtin_amdgcn_s_setprio(0); } while (0)
; #define PG8_WAIT_V(n) asm volatile("s_waitcnt vmcnt(" #n ")" ::: "memory")
; #define PG8_WAIT_L(n) asm volatile("s_waitcnt lgkmcnt(" #n ")" ::: "memory")
; #define PG8_BAR __builtin_amdgcn_s_barrier()
; #define PG8_SCHED __builtin_amdgcn_sched_barrier(0)
; template <class Epi, class Sched, bool ALIGN_EPI = false, bool SP2 = false>
; __device__ __forceinline__ void gemm_phase(PG8_LAS unsigned char* lds, const Gemm g, const Sched& S, const Epi& E) {
;     ...
;         for (int t = 0; t < nt; t += 2) {
;     ...
;             PG8_LDA(At, 1, 1); PG8_STAGE(PG8_SB(1, 0), b3, voffB); PG8_STAGE(PG8_SB(1, 1), b3 + hstep, voffB); PG8_STAGE(PG8_SA(1, 0), a3, voffA);
;             PG8_WAIT_V(8); PG8_WAIT_L(0); PG8_BAR; PG8_MMA(1, 0, At, B0); PG8_MMA(1, 1, At, B1); PG8_BAR; PG8_SCHED;
	s_add_i32 s48, s57, s0
	v_lshl_add_u64 v[148:149], v[148:149], 0, s[26:27]
	s_mov_b32 m0, s48
	ds_read_b128 v[192:195], v159 offset:49152
	ds_read_b128 v[198:201], v159 offset:50176
	ds_read_b128 v[202:205], v159 offset:51200
	ds_read_b128 v[206:209], v159 offset:52224
	ds_read_b128 v[210:213], v159 offset:53248
	ds_read_b128 v[214:217], v159 offset:54272
	ds_read_b128 v[218:221], v159 offset:55296
	ds_read_b128 v[222:225], v159 offset:56320
	global_load_lds_dwordx4 v[148:149], off
	s_add_i32 m0, s48, 0x2000
	s_add_u32 s46, s46, 0x40080
	v_lshl_add_u64 v[148:149], v[152:153], 0, s[26:27]
	s_addc_u32 s47, s47, 0
	s_add_i32 s48, s58, s0
	global_load_lds_dwordx4 v[148:149], off
	v_lshl_add_u64 v[148:149], s[46:47], 0, v[138:139]
	s_mov_b32 m0, s48
	s_nop 0
	global_load_lds_dwordx4 v[148:149], off
	v_lshl_add_u64 v[148:149], s[46:47], 0, v[78:79]
	s_add_i32 m0, s48, 0x2000
	s_nop 0
	global_load_lds_dwordx4 v[148:149], off
	v_lshl_add_u64 v[148:149], v[156:157], 0, s[26:27]
	s_mov_b32 m0, s24
	s_nop 0
	global_load_lds_dwordx4 v[148:149], off
	v_lshl_add_u64 v[148:149], v[226:227], 0, s[26:27]
	s_mov_b32 m0, s25
	s_nop 0
	global_load_lds_dwordx4 v[148:149], off
	s_waitcnt vmcnt(8)
	s_waitcnt lgkmcnt(0)
	s_barrier
	s_setprio 1
	s_waitcnt lgkmcnt(0)
	v_mfma_f32_16x16x32_bf16 v[62:65], v[160:163], v[192:195], v[62:65]
	v_mfma_f32_16x16x32_bf16 v[58:61], v[168:171], v[192:195], v[58:61]
	v_mfma_f32_16x16x32_bf16 v[50:53], v[160:163], v[202:205], v[50:53]
	v_mfma_f32_16x16x32_bf16 v[42:45], v[168:171], v[202:205], v[42:45]
	v_mfma_f32_16x16x32_bf16 v[34:37], v[160:163], v[210:213], v[34:37]
	v_mfma_f32_16x16x32_bf16 v[26:29], v[168:171], v[210:213], v[26:29]
	v_mfma_f32_16x16x32_bf16 v[18:21], v[160:163], v[218:221], v[18:21]
	v_mfma_f32_16x16x32_bf16 v[10:13], v[168:171], v[218:221], v[10:13]
	v_mfma_f32_16x16x32_bf16 v[62:65], v[164:167], v[198:201], v[62:65]
	v_mfma_f32_16x16x32_bf16 v[58:61], v[172:175], v[198:201], v[58:61]
	v_mfma_f32_16x16x32_bf16 v[50:53], v[164:167], v[206:209], v[50:53]
	v_mfma_f32_16x16x32_bf16 v[42:45], v[172:175], v[206:209], v[42:45]
	v_mfma_f32_16x16x32_bf16 v[34:37], v[164:167], v[214:217], v[34:37]
	v_mfma_f32_16x16x32_bf16 v[26:29], v[172:175], v[214:217], v[26:29]
	v_mfma_f32_16x16x32_bf16 v[18:21], v[164:167], v[222:225], v[18:21]
	v_mfma_f32_16x16x32_bf16 v[10:13], v[172:175], v[222:225], v[10:13]
	v_mfma_f32_16x16x32_bf16 v[54:57], v[176:179], v[192:195], v[54:57]
	v_mfma_f32_16x16x32_bf16 v[46:49], v[184:187], v[192:195], v[46:49]
	v_mfma_f32_16x16x32_bf16 v[38:41], v[176:179], v[202:205], v[38:41]
	v_mfma_f32_16x16x32_bf16 v[30:33], v[184:187], v[202:205], v[30:33]
	v_mfma_f32_16x16x32_bf16 v[22:25], v[176:179], v[210:213], v[22:25]
	v_mfma_f32_16x16x32_bf16 v[14:17], v[184:187], v[210:213], v[14:17]
	v_mfma_f32_16x16x32_bf16 v[6:9], v[176:179], v[218:221], v[6:9]
	v_mfma_f32_16x16x32_bf16 v[2:5], v[184:187], v[218:221], v[2:5]
	v_mfma_f32_16x16x32_bf16 v[54:57], v[180:183], v[198:201], v[54:57]
	v_mfma_f32_16x16x32_bf16 v[46:49], v[188:191], v[198:201], v[46:49]
	v_mfma_f32_16x16x32_bf16 v[38:41], v[180:183], v[206:209], v[38:41]
	v_mfma_f32_16x16x32_bf16 v[30:33], v[188:191], v[206:209], v[30:33]
	v_mfma_f32_16x16x32_bf16 v[22:25], v[180:183], v[214:217], v[22:25]
	v_mfma_f32_16x16x32_bf16 v[14:17], v[188:191], v[214:217], v[14:17]
	v_mfma_f32_16x16x32_bf16 v[6:9], v[180:183], v[222:225], v[6:9]
	v_mfma_f32_16x16x32_bf16 v[2:5], v[188:191], v[222:225], v[2:5]
	s_setprio 0
	s_barrier
	s_add_i32 s56, s56, 2
	s_add_u32 s44, s44, 0x100
	s_addc_u32 s45, s45, 0
	s_add_u32 s54, s54, 0x100
	s_addc_u32 s55, s55, 0
	s_cmp_gt_u32 s56, 13

; #define PG8_STAGE(bufoff, gbase, voff) do { _Pragma("unroll") for (int _i = 0; _i < 2; ++_i) \
;         __builtin_amdgcn_global_load_lds((const unsigned*)((const char*)(gbase) + (voff)[_i]), (PG8_LAS unsigned*)(lds + (bufoff) + ldsw + _i * 8192), 16, 0, 0); } while (0)
; #define PG8_LDA(dst, b, h) do { _Pragma("unroll") for (int m = 0; m < 4; ++m) _Pragma("unroll") for (int k = 0; k < 2; ++k) dst[m][k] = *(const PG8_LAS bf16x8*)(lds + PG8_SA(b, h) + aoff + m * 2048 + k * 1024); } while (0)
; #define PG8_LDB(dst, b, h) do { _Pragma("unroll") for (int n = 0; n < 2; ++n) _Pragma("unroll") for (int k = 0; k < 2; ++k) dst[n][k] = *(const PG8_LAS bf16x8*)(lds + PG8_SB(b, h) + boff + n * 2048 + k * 1024); } while (0)
; #define PG8_MMA(ai, bj, At, Bt) do { __builtin_amdgcn_s_setprio(1); _Pragma("unroll") for (int m = 0; m < 4; ++m) _Pragma("unroll") for (int n = 0; n < 2; ++n) _Pragma("unroll") for (int k = 0; k < 2; ++k) \
;         acc[ai][bj][m][n] = __builtin_amdgcn_mfma_f32_16x16x32_bf16(Bt[n][k], At[m][k], acc[ai][bj][m][n], 0, 0, 0); __builtin_amdgcn_s_setprio(0); } while (0)
; #define PG8_WAIT_V(n) asm volatile("s_waitcnt vmcnt(" #n ")" ::: "memory")
; template <class Epi, class Sched, bool ALIGN_EPI = false, bool SP2 = false>
; __device__ __forceinline__ void gemm_phase(PG8_LAS unsigned char* lds, const Gemm g, const Sched& S, const Epi& E) {
;     ...
;         const char* nA = has_next ? (const char*)g.A + (size_t)nxt.pm * tstepA : cA; const char* nB = has_next ? (const char*)g.Bt + (size_t)nxt.pn * tstep : cB;
;         for (int t = 0; t < nt; t += 2) {
;             const bool last = (t == nt - 2);
;             const char* a1 = cA + (size_t)(t + 1) * kstep;
;             const char* a2 = last ? nA : cA + (size_t)(t + 2) * kstep; const char* b2 = last ? nB : cB + (size_t)(t + 2) * kstep;
;             const char* a3 = a2 + kstep; const char* b3 = b2 + kstep;
;             if (last && has_next) S.a_ready(nxt);
;             if constexpr (SP2) {
;             PG8_LDB(B0, 0, 0); PG8_LDB(B1, 0, 1); PG8_SCHED; PG8_LDA(At, 0, 0); PG8_STAGE(PG8_SA(1, 1), a1 + hstepA, voffA);
;             PG8_WAIT_V(8); PG8_WAIT_L(0); PG8_BAR; PG8_MMA(0, 0, At, B0); PG8_MMA(0, 1, At, B1); PG8_BAR; PG8_SCHED;
;             PG8_LDA(At, 0, 1); PG8_STAGE(PG8_SB(0, 0), b2, voffB); PG8_STAGE(PG8_SB(0, 1), b2 + hstep, voffB); PG8_STAGE(PG8_SA(0, 0), a2, voffA);
.LBB0_526:
	s_add_u32 s42, s42, 0x80
	s_addc_u32 s43, s43, 0
	s_add_u32 s87, s72, 0x100
	s_addc_u32 s88, s73, 0
	s_mov_b32 s72, 0
	s_waitcnt vmcnt(0)
	s_add_i32 s89, s72, 2
	s_add_u32 s90, s42, 0x80
	s_addc_u32 s73, s43, 0
	s_add_i32 s92, 0, 0x10000
	s_cmp_eq_u32 s79, s72
	s_cselect_b32 s73, s7, s73
	s_cselect_b32 s72, s6, s90
	v_add_u32_e32 v150, s92, v151
	s_cselect_b32 s91, s71, s88
	s_cselect_b32 s90, s70, s87
	s_add_i32 s93, 0, 0x14000
	ds_read_b128 v[146:149], v150
	ds_read_b128 v[156:159], v150 offset:1024
	ds_read_b128 v[160:163], v150 offset:2048
	ds_read_b128 v[164:167], v150 offset:3072
	v_add_u32_e32 v150, s93, v151
	ds_read_b128 v[168:171], v150
	ds_read_b128 v[172:175], v150 offset:1024
	ds_read_b128 v[176:179], v150 offset:2048
	ds_read_b128 v[180:183], v150 offset:3072
	v_lshl_add_u64 v[218:219], s[42:43], 0, v[142:143]
	s_add_i32 m0, s25, 0xc000
	ds_read_b128 v[184:187], v155
	ds_read_b128 v[188:191], v155 offset:1024
	ds_read_b128 v[192:195], v155 offset:2048
	ds_read_b128 v[198:201], v155 offset:3072
	ds_read_b128 v[202:205], v155 offset:4096
	ds_read_b128 v[206:209], v155 offset:5120
	ds_read_b128 v[210:213], v155 offset:6144
	ds_read_b128 v[214:217], v155 offset:7168
	global_load_lds_dwordx4 v[218:219], off
	v_lshl_add_u64 v[218:219], s[42:43], 0, v[144:145]
	s_add_i32 m0, s25, 0xe000
	s_nop 0
	global_load_lds_dwordx4 v[218:219], off
	s_waitcnt vmcnt(8)
	s_waitcnt lgkmcnt(0)
	s_barrier
	s_setprio 1
	s_waitcnt lgkmcnt(0)
	v_mfma_f32_16x16x32_bf16 v[132:135], v[146:149], v[184:187], 0
	v_mfma_f32_16x16x32_bf16 v[128:131], v[160:163], v[184:187], 0
	v_mfma_f32_16x16x32_bf16 v[116:119], v[146:149], v[192:195], 0
	v_mfma_f32_16x16x32_bf16 v[112:115], v[160:163], v[192:195], 0
	v_mfma_f32_16x16x32_bf16 v[100:103], v[146:149], v[202:205], 0
	v_mfma_f32_16x16x32_bf16 v[96:99], v[160:163], v[202:205], 0
	v_mfma_f32_16x16x32_bf16 v[84:87], v[146:149], v[210:213], 0
	v_mfma_f32_16x16x32_bf16 v[74:77], v[160:163], v[210:213], 0
	v_mfma_f32_16x16x32_bf16 v[132:135], v[156:159], v[188:191], v[132:135]
	v_mfma_f32_16x16x32_bf16 v[128:131], v[164:167], v[188:191], v[128:131]
	v_mfma_f32_16x16x32_bf16 v[116:119], v[156:159], v[198:201], v[116:119]
	v_mfma_f32_16x16x32_bf16 v[112:115], v[164:167], v[198:201], v[112:115]
	v_mfma_f32_16x16x32_bf16 v[100:103], v[156:159], v[206:209], v[100:103]
	v_mfma_f32_16x16x32_bf16 v[96:99], v[164:167], v[206:209], v[96:99]
	v_mfma_f32_16x16x32_bf16 v[84:87], v[156:159], v[214:217], v[84:87]
	v_mfma_f32_16x16x32_bf16 v[74:77], v[164:167], v[214:217], v[74:77]
	v_mfma_f32_16x16x32_bf16 v[124:127], v[168:171], v[184:187], 0
	v_mfma_f32_16x16x32_bf16 v[120:123], v[176:179], v[184:187], 0
	v_mfma_f32_16x16x32_bf16 v[108:111], v[168:171], v[192:195], 0
	v_mfma_f32_16x16x32_bf16 v[104:107], v[176:179], v[192:195], 0
	v_mfma_f32_16x16x32_bf16 v[92:95], v[168:171], v[202:205], 0
	v_mfma_f32_16x16x32_bf16 v[88:91], v[176:179], v[202:205], 0
	v_mfma_f32_16x16x32_bf16 v[70:73], v[168:171], v[210:213], 0
	v_mfma_f32_16x16x32_bf16 v[66:69], v[176:179], v[210:213], 0
	v_mfma_f32_16x16x32_bf16 v[124:127], v[172:175], v[188:191], v[124:127]
	v_mfma_f32_16x16x32_bf16 v[120:123], v[180:183], v[188:191], v[120:123]
	v_mfma_f32_16x16x32_bf16 v[108:111], v[172:175], v[198:201], v[108:111]
	v_mfma_f32_16x16x32_bf16 v[104:107], v[180:183], v[198:201], v[104:107]
	v_mfma_f32_16x16x32_bf16 v[92:95], v[172:175], v[206:209], v[92:95]
	v_mfma_f32_16x16x32_bf16 v[88:91], v[180:183], v[206:209], v[88:91]
	v_mfma_f32_16x16x32_bf16 v[70:73], v[172:175], v[214:217], v[70:73]
	v_mfma_f32_16x16x32_bf16 v[66:69], v[180:183], v[214:217], v[66:69]
	s_setprio 0
	s_barrier
	s_add_i32 s92, s92, s21
	v_lshl_add_u64 v[218:219], s[90:91], 0, v[136:137]
	s_mov_b32 m0, s92
	ds_read_b128 v[184:187], v155 offset:16384
	ds_read_b128 v[188:191], v155 offset:17408
	ds_read_b128 v[192:195], v155 offset:18432
	ds_read_b128 v[198:201], v155 offset:19456
	ds_read_b128 v[202:205], v155 offset:20480
	ds_read_b128 v[206:209], v155 offset:21504
	ds_read_b128 v[210:213], v155 offset:22528
	ds_read_b128 v[214:217], v155 offset:23552
	global_load_lds_dwordx4 v[218:219], off
	s_add_i32 m0, s92, 0x2000
	v_lshl_add_u64 v[220:221], s[90:91], 0, v[140:141]
	s_add_u32 s90, s90, s0
	s_addc_u32 s91, s91, 0
	s_add_i32 s92, s93, s21
	global_load_lds_dwordx4 v[220:221], off
	v_lshl_add_u64 v[222:223], s[90:91], 0, v[136:137]
	s_mov_b32 m0, s92
	v_lshl_add_u64 v[224:225], s[90:91], 0, v[140:141]
	global_load_lds_dwordx4 v[222:223], off
	s_add_i32 m0, s92, 0x2000
	v_lshl_add_u64 v[226:227], s[72:73], 0, v[78:79]
	global_load_lds_dwordx4 v[224:225], off
	s_mov_b32 m0, s25
	v_lshl_add_u64 v[236:237], s[72:73], 0, v[138:139]
	global_load_lds_dwordx4 v[226:227], off
	s_mov_b32 m0, s37
	s_nop 0
	global_load_lds_dwordx4 v[236:237], off
	s_waitcnt vmcnt(8)
	s_waitcnt lgkmcnt(0)
	s_barrier
; #define PG8_STAGE(bufoff, gbase, voff) do { _Pragma("unroll") for (int _i = 0; _i < 2; ++_i) \
;         __builtin_amdgcn_global_load_lds((const unsigned*)((const char*)(gbase) + (voff)[_i]), (PG8_LAS unsigned*)(lds + (bufoff) + ldsw + _i * 8192), 16, 0, 0); } while (0)
; #define PG8_LDA(dst, b, h) do { _Pragma("unroll") for (int m = 0; m < 4; ++m) _Pragma("unroll") for (int k = 0; k < 2; ++k) dst[m][k] = *(const PG8_LAS bf16x8*)(lds + PG8_SA(b, h) + aoff + m * 2048 + k * 1024); } while (0)
; #define PG8_LDB(dst, b, h) do { _Pragma("unroll") for (int n = 0; n < 2; ++n) _Pragma("unroll") for (int k = 0; k < 2; ++k) dst[n][k] = *(const PG8_LAS bf16x8*)(lds + PG8_SB(b, h) + boff + n * 2048 + k * 1024); } while (0)
; #define PG8_MMA(ai, bj, At, Bt) do { __builtin_amdgcn_s_setprio(1); _Pragma("unroll") for (int m = 0; m < 4; ++m) _Pragma("unroll") for (int n = 0; n < 2; ++n) _Pragma("unroll") for (int k = 0; k < 2; ++k) \
;         acc[ai][bj][m][n] = __builtin_amdgcn_mfma_f32_16x16x32_bf16(Bt[n][k], At[m][k], acc[ai][bj][m][n], 0, 0, 0); __builtin_amdgcn_s_setprio(0); } while (0)
; #define PG8_WAIT_V(n) asm volatile("s_waitcnt vmcnt(" #n ")" ::: "memory")
; #define PG8_WAIT_L(n) asm volatile("s_waitcnt lgkmcnt(" #n ")" ::: "memory")
; #define PG8_BAR __builtin_amdgcn_s_barrier()
; #define PG8_SCHED __builtin_amdgcn_sched_barrier(0)
; template <class Epi, class Sched, bool ALIGN_EPI = false, bool SP2 = false>
; __device__ __forceinline__ void gemm_phase(PG8_LAS unsigned char* lds, const Gemm g, const Sched& S, const Epi& E) {
;     ...
;             PG8_WAIT_V(8); PG8_WAIT_L(0); PG8_BAR; PG8_MMA(1, 0, At, B0); PG8_MMA(1, 1, At, B1); PG8_BAR; PG8_SCHED;
;             PG8_LDB(B0, 1, 0); PG8_LDB(B1, 1, 1); PG8_SCHED; PG8_LDA(At, 1, 0); PG8_STAGE(PG8_SA(0, 1), a2 + hstepA, voffA);
;             PG8_WAIT_V(8); PG8_WAIT_L(0); PG8_BAR; PG8_MMA(0, 0, At, B0); PG8_MMA(0, 1, At, B1); PG8_BAR; PG8_SCHED;
	s_setprio 1
	s_waitcnt lgkmcnt(0)
	v_mfma_f32_16x16x32_bf16 v[62:65], v[146:149], v[184:187], 0
	v_mfma_f32_16x16x32_bf16 v[58:61], v[160:163], v[184:187], 0
	v_mfma_f32_16x16x32_bf16 v[46:49], v[146:149], v[192:195], 0
	v_mfma_f32_16x16x32_bf16 v[42:45], v[160:163], v[192:195], 0
	v_mfma_f32_16x16x32_bf16 v[30:33], v[146:149], v[202:205], 0
	v_mfma_f32_16x16x32_bf16 v[26:29], v[160:163], v[202:205], 0
	v_mfma_f32_16x16x32_bf16 v[14:17], v[146:149], v[210:213], 0
	v_mfma_f32_16x16x32_bf16 v[10:13], v[160:163], v[210:213], 0
	v_mfma_f32_16x16x32_bf16 v[62:65], v[156:159], v[188:191], v[62:65]
	v_mfma_f32_16x16x32_bf16 v[58:61], v[164:167], v[188:191], v[58:61]
	v_mfma_f32_16x16x32_bf16 v[46:49], v[156:159], v[198:201], v[46:49]
	v_mfma_f32_16x16x32_bf16 v[42:45], v[164:167], v[198:201], v[42:45]
	v_mfma_f32_16x16x32_bf16 v[30:33], v[156:159], v[206:209], v[30:33]
	v_mfma_f32_16x16x32_bf16 v[26:29], v[164:167], v[206:209], v[26:29]
	v_mfma_f32_16x16x32_bf16 v[14:17], v[156:159], v[214:217], v[14:17]
	v_mfma_f32_16x16x32_bf16 v[10:13], v[164:167], v[214:217], v[10:13]
	v_mfma_f32_16x16x32_bf16 v[54:57], v[168:171], v[184:187], 0
	v_mfma_f32_16x16x32_bf16 v[50:53], v[176:179], v[184:187], 0
	v_mfma_f32_16x16x32_bf16 v[38:41], v[168:171], v[192:195], 0
	v_mfma_f32_16x16x32_bf16 v[34:37], v[176:179], v[192:195], 0
	v_mfma_f32_16x16x32_bf16 v[22:25], v[168:171], v[202:205], 0
	v_mfma_f32_16x16x32_bf16 v[18:21], v[176:179], v[202:205], 0
	v_mfma_f32_16x16x32_bf16 v[6:9], v[168:171], v[210:213], 0
	v_mfma_f32_16x16x32_bf16 v[2:5], v[176:179], v[210:213], 0
	v_mfma_f32_16x16x32_bf16 v[54:57], v[172:175], v[188:191], v[54:57]
	v_mfma_f32_16x16x32_bf16 v[50:53], v[180:183], v[188:191], v[50:53]
	v_mfma_f32_16x16x32_bf16 v[38:41], v[172:175], v[198:201], v[38:41]
	v_mfma_f32_16x16x32_bf16 v[34:37], v[180:183], v[198:201], v[34:37]
	v_mfma_f32_16x16x32_bf16 v[22:25], v[172:175], v[206:209], v[22:25]
	v_mfma_f32_16x16x32_bf16 v[18:21], v[180:183], v[206:209], v[18:21]
	v_mfma_f32_16x16x32_bf16 v[6:9], v[172:175], v[214:217], v[6:9]
	v_mfma_f32_16x16x32_bf16 v[2:5], v[180:183], v[214:217], v[2:5]
	s_setprio 0
	s_barrier
	s_add_i32 s90, 0, 0x18000
	v_add_u32_e32 v150, s90, v151
	s_add_i32 s91, 0, 0x1c000
	ds_read_b128 v[146:149], v150
	ds_read_b128 v[156:159], v150 offset:1024
	ds_read_b128 v[160:163], v150 offset:2048
	ds_read_b128 v[164:167], v150 offset:3072
	v_add_u32_e32 v150, s91, v151
	ds_read_b128 v[168:171], v150
	ds_read_b128 v[172:175], v150 offset:1024
	ds_read_b128 v[176:179], v150 offset:2048
	ds_read_b128 v[180:183], v150 offset:3072
	s_add_u32 s72, s72, s0
	s_addc_u32 s73, s73, 0
	s_mov_b32 m0, s74
	v_lshl_add_u64 v[238:239], s[72:73], 0, v[78:79]
	ds_read_b128 v[184:187], v155 offset:32768
	ds_read_b128 v[188:191], v155 offset:33792
	ds_read_b128 v[192:195], v155 offset:34816
	ds_read_b128 v[198:201], v155 offset:35840
	ds_read_b128 v[202:205], v155 offset:36864
	ds_read_b128 v[206:209], v155 offset:37888
	ds_read_b128 v[210:213], v155 offset:38912
	ds_read_b128 v[214:217], v155 offset:39936
	global_load_lds_dwordx4 v[238:239], off
	v_lshl_add_u64 v[238:239], s[72:73], 0, v[138:139]
	s_mov_b32 m0, s75
	s_nop 0
	global_load_lds_dwordx4 v[238:239], off
	s_waitcnt vmcnt(8)
	s_waitcnt lgkmcnt(0)
	s_barrier
	s_setprio 1
	s_waitcnt lgkmcnt(0)
	v_mfma_f32_16x16x32_bf16 v[132:135], v[146:149], v[184:187], v[132:135]
	v_mfma_f32_16x16x32_bf16 v[128:131], v[160:163], v[184:187], v[128:131]
	v_mfma_f32_16x16x32_bf16 v[116:119], v[146:149], v[192:195], v[116:119]
	v_mfma_f32_16x16x32_bf16 v[112:115], v[160:163], v[192:195], v[112:115]
	v_mfma_f32_16x16x32_bf16 v[100:103], v[146:149], v[202:205], v[100:103]
	v_mfma_f32_16x16x32_bf16 v[96:99], v[160:163], v[202:205], v[96:99]
	v_mfma_f32_16x16x32_bf16 v[84:87], v[146:149], v[210:213], v[84:87]
	v_mfma_f32_16x16x32_bf16 v[74:77], v[160:163], v[210:213], v[74:77]
	v_mfma_f32_16x16x32_bf16 v[132:135], v[156:159], v[188:191], v[132:135]
	v_mfma_f32_16x16x32_bf16 v[128:131], v[164:167], v[188:191], v[128:131]
	v_mfma_f32_16x16x32_bf16 v[116:119], v[156:159], v[198:201], v[116:119]
	v_mfma_f32_16x16x32_bf16 v[112:115], v[164:167], v[198:201], v[112:115]
	v_mfma_f32_16x16x32_bf16 v[100:103], v[156:159], v[206:209], v[100:103]
	v_mfma_f32_16x16x32_bf16 v[96:99], v[164:167], v[206:209], v[96:99]
	v_mfma_f32_16x16x32_bf16 v[84:87], v[156:159], v[214:217], v[84:87]
	v_mfma_f32_16x16x32_bf16 v[74:77], v[164:167], v[214:217], v[74:77]
	v_mfma_f32_16x16x32_bf16 v[124:127], v[168:171], v[184:187], v[124:127]
	v_mfma_f32_16x16x32_bf16 v[120:123], v[176:179], v[184:187], v[120:123]
	v_mfma_f32_16x16x32_bf16 v[108:111], v[168:171], v[192:195], v[108:111]
	v_mfma_f32_16x16x32_bf16 v[104:107], v[176:179], v[192:195], v[104:107]
	v_mfma_f32_16x16x32_bf16 v[92:95], v[168:171], v[202:205], v[92:95]
	v_mfma_f32_16x16x32_bf16 v[88:91], v[176:179], v[202:205], v[88:91]
	v_mfma_f32_16x16x32_bf16 v[70:73], v[168:171], v[210:213], v[70:73]
	v_mfma_f32_16x16x32_bf16 v[66:69], v[176:179], v[210:213], v[66:69]
	v_mfma_f32_16x16x32_bf16 v[124:127], v[172:175], v[188:191], v[124:127]
	v_mfma_f32_16x16x32_bf16 v[120:123], v[180:183], v[188:191], v[120:123]
	v_mfma_f32_16x16x32_bf16 v[108:111], v[172:175], v[198:201], v[108:111]
	v_mfma_f32_16x16x32_bf16 v[104:107], v[180:183], v[198:201], v[104:107]
	v_mfma_f32_16x16x32_bf16 v[92:95], v[172:175], v[206:209], v[92:95]
	v_mfma_f32_16x16x32_bf16 v[88:91], v[180:183], v[206:209], v[88:91]
	v_mfma_f32_16x16x32_bf16 v[70:73], v[172:175], v[214:217], v[70:73]
	v_mfma_f32_16x16x32_bf16 v[66:69], v[180:183], v[214:217], v[66:69]
	s_setprio 0
	s_barrier
; #define PG8_STAGE(bufoff, gbase, voff) do { _Pragma("unroll") for (int _i = 0; _i < 2; ++_i) \
;         __builtin_amdgcn_global_load_lds((const unsigned*)((const char*)(gbase) + (voff)[_i]), (PG8_LAS unsigned*)(lds + (bufoff) + ldsw + _i * 8192), 16, 0, 0); } while (0)
; #define PG8_LDA(dst, b, h) do { _Pragma("unroll") for (int m = 0; m < 4; ++m) _Pragma("unroll") for (int k = 0; k < 2; ++k) dst[m][k] = *(const PG8_LAS bf16x8*)(lds + PG8_SA(b, h) + aoff + m * 2048 + k * 1024); } while (0)
; #define PG8_MMA(ai, bj, At, Bt) do { __builtin_amdgcn_s_setprio(1); _Pragma("unroll") for (int m = 0; m < 4; ++m) _Pragma("unroll") for (int n = 0; n < 2; ++n) _Pragma("unroll") for (int k = 0; k < 2; ++k) \
;         acc[ai][bj][m][n] = __builtin_amdgcn_mfma_f32_16x16x32_bf16(Bt[n][k], At[m][k], acc[ai][bj][m][n], 0, 0, 0); __builtin_amdgcn_s_setprio(0); } while (0)
; #define PG8_WAIT_V(n) asm volatile("s_waitcnt vmcnt(" #n ")" ::: "memory")
; #define PG8_WAIT_L(n) asm volatile("s_waitcnt lgkmcnt(" #n ")" ::: "memory")
; #define PG8_BAR __builtin_amdgcn_s_barrier()
; #define PG8_SCHED __builtin_amdgcn_sched_barrier(0)
; template <class Epi, class Sched, bool ALIGN_EPI = false, bool SP2 = false>
; __device__ __forceinline__ void gemm_phase(PG8_LAS unsigned char* lds, const Gemm g, const Sched& S, const Epi& E) {
;     ...
;         for (int t = 0; t < nt; t += 2) {
;     ...
;             PG8_LDA(At, 1, 1); PG8_STAGE(PG8_SB(1, 0), b3, voffB); PG8_STAGE(PG8_SB(1, 1), b3 + hstep, voffB); PG8_STAGE(PG8_SA(1, 0), a3, voffA);
;             PG8_WAIT_V(8); PG8_WAIT_L(0); PG8_BAR; PG8_MMA(1, 0, At, B0); PG8_MMA(1, 1, At, B1); PG8_BAR; PG8_SCHED;
	s_add_i32 s72, s90, s21
	v_lshl_add_u64 v[218:219], v[218:219], 0, s[26:27]
	s_mov_b32 m0, s72
	ds_read_b128 v[184:187], v155 offset:49152
	ds_read_b128 v[188:191], v155 offset:50176
	ds_read_b128 v[192:195], v155 offset:51200
	ds_read_b128 v[198:201], v155 offset:52224
	ds_read_b128 v[202:205], v155 offset:53248
	ds_read_b128 v[206:209], v155 offset:54272
	ds_read_b128 v[210:213], v155 offset:55296
	ds_read_b128 v[214:217], v155 offset:56320
	global_load_lds_dwordx4 v[218:219], off
	v_lshl_add_u64 v[218:219], v[220:221], 0, s[26:27]
	s_add_i32 m0, s72, 0x2000
	s_add_i32 s72, s91, s21
	global_load_lds_dwordx4 v[218:219], off
	v_lshl_add_u64 v[218:219], v[222:223], 0, s[26:27]
	s_mov_b32 m0, s72
	s_nop 0
	global_load_lds_dwordx4 v[218:219], off
	v_lshl_add_u64 v[218:219], v[224:225], 0, s[26:27]
	s_add_i32 m0, s72, 0x2000
	s_nop 0
	global_load_lds_dwordx4 v[218:219], off
	v_lshl_add_u64 v[218:219], v[226:227], 0, s[26:27]
	s_mov_b32 m0, s76
	s_nop 0
	global_load_lds_dwordx4 v[218:219], off
	v_lshl_add_u64 v[218:219], v[236:237], 0, s[26:27]
	s_mov_b32 m0, s77
	s_nop 0
	global_load_lds_dwordx4 v[218:219], off
	s_waitcnt vmcnt(8)
	s_waitcnt lgkmcnt(0)
	s_barrier
	s_setprio 1
	s_waitcnt lgkmcnt(0)
	v_mfma_f32_16x16x32_bf16 v[62:65], v[146:149], v[184:187], v[62:65]
	v_mfma_f32_16x16x32_bf16 v[58:61], v[160:163], v[184:187], v[58:61]
	v_mfma_f32_16x16x32_bf16 v[46:49], v[146:149], v[192:195], v[46:49]
	v_mfma_f32_16x16x32_bf16 v[42:45], v[160:163], v[192:195], v[42:45]
	v_mfma_f32_16x16x32_bf16 v[30:33], v[146:149], v[202:205], v[30:33]
	v_mfma_f32_16x16x32_bf16 v[26:29], v[160:163], v[202:205], v[26:29]
	v_mfma_f32_16x16x32_bf16 v[14:17], v[146:149], v[210:213], v[14:17]
	v_mfma_f32_16x16x32_bf16 v[10:13], v[160:163], v[210:213], v[10:13]
	v_mfma_f32_16x16x32_bf16 v[62:65], v[156:159], v[188:191], v[62:65]
	v_mfma_f32_16x16x32_bf16 v[58:61], v[164:167], v[188:191], v[58:61]
	v_mfma_f32_16x16x32_bf16 v[46:49], v[156:159], v[198:201], v[46:49]
	v_mfma_f32_16x16x32_bf16 v[42:45], v[164:167], v[198:201], v[42:45]
	v_mfma_f32_16x16x32_bf16 v[30:33], v[156:159], v[206:209], v[30:33]
	v_mfma_f32_16x16x32_bf16 v[26:29], v[164:167], v[206:209], v[26:29]
	v_mfma_f32_16x16x32_bf16 v[14:17], v[156:159], v[214:217], v[14:17]
	v_mfma_f32_16x16x32_bf16 v[10:13], v[164:167], v[214:217], v[10:13]
	v_mfma_f32_16x16x32_bf16 v[54:57], v[168:171], v[184:187], v[54:57]
	v_mfma_f32_16x16x32_bf16 v[50:53], v[176:179], v[184:187], v[50:53]
	v_mfma_f32_16x16x32_bf16 v[38:41], v[168:171], v[192:195], v[38:41]
	v_mfma_f32_16x16x32_bf16 v[34:37], v[176:179], v[192:195], v[34:37]
	v_mfma_f32_16x16x32_bf16 v[22:25], v[168:171], v[202:205], v[22:25]
	v_mfma_f32_16x16x32_bf16 v[18:21], v[176:179], v[202:205], v[18:21]
	v_mfma_f32_16x16x32_bf16 v[6:9], v[168:171], v[210:213], v[6:9]
	v_mfma_f32_16x16x32_bf16 v[2:5], v[176:179], v[210:213], v[2:5]
	v_mfma_f32_16x16x32_bf16 v[54:57], v[172:175], v[188:191], v[54:57]
	v_mfma_f32_16x16x32_bf16 v[50:53], v[180:183], v[188:191], v[50:53]
	v_mfma_f32_16x16x32_bf16 v[38:41], v[172:175], v[198:201], v[38:41]
	v_mfma_f32_16x16x32_bf16 v[34:37], v[180:183], v[198:201], v[34:37]
	v_mfma_f32_16x16x32_bf16 v[22:25], v[172:175], v[206:209], v[22:25]
	v_mfma_f32_16x16x32_bf16 v[18:21], v[180:183], v[206:209], v[18:21]
	v_mfma_f32_16x16x32_bf16 v[6:9], v[172:175], v[214:217], v[6:9]
	v_mfma_f32_16x16x32_bf16 v[2:5], v[180:183], v[214:217], v[2:5]
	s_setprio 0
	s_barrier
	s_add_u32 s42, s42, 0x100
	s_addc_u32 s43, s43, 0
	s_add_u32 s87, s87, 0x100
	s_addc_u32 s88, s88, 0
	s_cmp_ge_u32 s89, s78
	s_mov_b32 s72, s89

; #define PG8_STAGE(bufoff, gbase, voff) do { _Pragma("unroll") for (int _i = 0; _i < 2; ++_i) \
;         __builtin_amdgcn_global_load_lds((const unsigned*)((const char*)(gbase) + (voff)[_i]), (PG8_LAS unsigned*)(lds + (bufoff) + ldsw + _i * 8192), 16, 0, 0); } while (0)
; #define PG8_LDA(dst, b, h) do { _Pragma("unroll") for (int m = 0; m < 4; ++m) _Pragma("unroll") for (int k = 0; k < 2; ++k) dst[m][k] = *(const PG8_LAS bf16x8*)(lds + PG8_SA(b, h) + aoff + m * 2048 + k * 1024); } while (0)
; #define PG8_LDB(dst, b, h) do { _Pragma("unroll") for (int n = 0; n < 2; ++n) _Pragma("unroll") for (int k = 0; k < 2; ++k) dst[n][k] = *(const PG8_LAS bf16x8*)(lds + PG8_SB(b, h) + boff + n * 2048 + k * 1024); } while (0)
; #define PG8_MMA(ai, bj, At, Bt) do { __builtin_amdgcn_s_setprio(1); _Pragma("unroll") for (int m = 0; m < 4; ++m) _Pragma("unroll") for (int n = 0; n < 2; ++n) _Pragma("unroll") for (int k = 0; k < 2; ++k) \
;         acc[ai][bj][m][n] = __builtin_amdgcn_mfma_f32_16x16x32_bf16(Bt[n][k], At[m][k], acc[ai][bj][m][n], 0, 0, 0); __builtin_amdgcn_s_setprio(0); } while (0)
; #define PG8_WAIT_V(n) asm volatile("s_waitcnt vmcnt(" #n ")" ::: "memory")
; template <class Epi, class Sched, bool ALIGN_EPI = false, bool SP2 = false>
; __device__ __forceinline__ void gemm_phase(PG8_LAS unsigned char* lds, const Gemm g, const Sched& S, const Epi& E) {
;     ...
;         const char* nA = has_next ? (const char*)g.A + (size_t)nxt.pm * tstepA : cA; const char* nB = has_next ? (const char*)g.Bt + (size_t)nxt.pn * tstep : cB;
;         for (int t = 0; t < nt; t += 2) {
;             const bool last = (t == nt - 2);
;             const char* a1 = cA + (size_t)(t + 1) * kstep;
;             const char* a2 = last ? nA : cA + (size_t)(t + 2) * kstep; const char* b2 = last ? nB : cB + (size_t)(t + 2) * kstep;
;             const char* a3 = a2 + kstep; const char* b3 = b2 + kstep;
;             if (last && has_next) S.a_ready(nxt);
;             if constexpr (SP2) {
;             PG8_LDB(B0, 0, 0); PG8_LDB(B1, 0, 1); PG8_SCHED; PG8_LDA(At, 0, 0); PG8_STAGE(PG8_SA(1, 1), a1 + hstepA, voffA);
;             PG8_WAIT_V(8); PG8_WAIT_L(0); PG8_BAR; PG8_MMA(0, 0, At, B0); PG8_MMA(0, 1, At, B1); PG8_BAR; PG8_SCHED;
;             PG8_LDA(At, 0, 1); PG8_STAGE(PG8_SB(0, 0), b2, voffB); PG8_STAGE(PG8_SB(0, 1), b2 + hstep, voffB); PG8_STAGE(PG8_SA(0, 0), a2, voffA);
.LBB0_599:
	s_add_u32 s46, s46, 0x80
	s_addc_u32 s47, s47, 0
	s_add_u32 s5, s48, 0x100
	s_addc_u32 s19, s49, 0
	s_mov_b32 s48, 0
	s_add_i32 s66, s48, 2
	s_add_u32 s67, s46, 0x80
	s_addc_u32 s49, s47, 0
	s_add_i32 s70, 0, 0x10000
	s_cmp_eq_u32 s62, s48
	s_cselect_b32 s49, s7, s49
	s_cselect_b32 s48, s6, s67
	s_cselect_b32 s69, s21, s19
	s_cselect_b32 s68, s20, s5
	s_add_i32 s67, 0, 0x14000
	v_add_u32_e32 v140, s70, v243
	v_add_u32_e32 v156, s67, v243
	ds_read_b128 v[120:123], v140
	ds_read_b128 v[132:135], v140 offset:1024
	ds_read_b128 v[136:139], v140 offset:2048
	ds_read_b128 v[140:143], v140 offset:3072
	ds_read_b128 v[144:147], v156
	ds_read_b128 v[148:151], v156 offset:1024
	ds_read_b128 v[152:155], v156 offset:2048
	ds_read_b128 v[156:159], v156 offset:3072
	v_lshl_add_u64 v[212:213], s[46:47], 0, v[204:205]
	s_add_i32 m0, s55, 0xc000
	ds_read_b128 v[160:163], v247
	ds_read_b128 v[164:167], v247 offset:1024
	ds_read_b128 v[168:171], v247 offset:2048
	ds_read_b128 v[176:179], v247 offset:3072
	ds_read_b128 v[184:187], v247 offset:4096
	ds_read_b128 v[188:191], v247 offset:5120
	ds_read_b128 v[192:195], v247 offset:6144
	ds_read_b128 v[208:211], v247 offset:7168
	global_load_lds_dwordx4 v[212:213], off
	v_lshl_add_u64 v[212:213], s[46:47], 0, v[206:207]
	s_add_i32 m0, s55, 0xe000
	s_nop 0
	global_load_lds_dwordx4 v[212:213], off
	s_waitcnt vmcnt(8)
	s_waitcnt lgkmcnt(0)
	s_barrier
	s_setprio 1
	s_waitcnt lgkmcnt(0)
	v_mfma_f32_16x16x32_bf16 v[180:183], v[120:123], v[160:163], 0
	v_mfma_f32_16x16x32_bf16 v[172:175], v[136:139], v[160:163], 0
	v_mfma_f32_16x16x32_bf16 v[116:119], v[120:123], v[168:171], 0
	v_mfma_f32_16x16x32_bf16 v[112:115], v[136:139], v[168:171], 0
	v_mfma_f32_16x16x32_bf16 v[100:103], v[120:123], v[184:187], 0
	v_mfma_f32_16x16x32_bf16 v[96:99], v[136:139], v[184:187], 0
	v_mfma_f32_16x16x32_bf16 v[84:87], v[120:123], v[192:195], 0
	v_mfma_f32_16x16x32_bf16 v[74:77], v[136:139], v[192:195], 0
	v_mfma_f32_16x16x32_bf16 v[180:183], v[132:135], v[164:167], v[180:183]
	v_mfma_f32_16x16x32_bf16 v[172:175], v[140:143], v[164:167], v[172:175]
	v_mfma_f32_16x16x32_bf16 v[116:119], v[132:135], v[176:179], v[116:119]
	v_mfma_f32_16x16x32_bf16 v[112:115], v[140:143], v[176:179], v[112:115]
	v_mfma_f32_16x16x32_bf16 v[100:103], v[132:135], v[188:191], v[100:103]
	v_mfma_f32_16x16x32_bf16 v[96:99], v[140:143], v[188:191], v[96:99]
	v_mfma_f32_16x16x32_bf16 v[84:87], v[132:135], v[208:211], v[84:87]
	v_mfma_f32_16x16x32_bf16 v[74:77], v[140:143], v[208:211], v[74:77]
	v_mfma_f32_16x16x32_bf16 v[128:131], v[144:147], v[160:163], 0
	v_mfma_f32_16x16x32_bf16 v[124:127], v[152:155], v[160:163], 0
	v_mfma_f32_16x16x32_bf16 v[108:111], v[144:147], v[168:171], 0
	v_mfma_f32_16x16x32_bf16 v[104:107], v[152:155], v[168:171], 0
	v_mfma_f32_16x16x32_bf16 v[92:95], v[144:147], v[184:187], 0
	v_mfma_f32_16x16x32_bf16 v[88:91], v[152:155], v[184:187], 0
	v_mfma_f32_16x16x32_bf16 v[70:73], v[144:147], v[192:195], 0
	v_mfma_f32_16x16x32_bf16 v[66:69], v[152:155], v[192:195], 0
	v_mfma_f32_16x16x32_bf16 v[128:131], v[148:151], v[164:167], v[128:131]
	v_mfma_f32_16x16x32_bf16 v[124:127], v[156:159], v[164:167], v[124:127]
	v_mfma_f32_16x16x32_bf16 v[108:111], v[148:151], v[176:179], v[108:111]
	v_mfma_f32_16x16x32_bf16 v[104:107], v[156:159], v[176:179], v[104:107]
	v_mfma_f32_16x16x32_bf16 v[92:95], v[148:151], v[188:191], v[92:95]
	v_mfma_f32_16x16x32_bf16 v[88:91], v[156:159], v[188:191], v[88:91]
	v_mfma_f32_16x16x32_bf16 v[70:73], v[148:151], v[208:211], v[70:73]
	v_mfma_f32_16x16x32_bf16 v[66:69], v[156:159], v[208:211], v[66:69]
	s_setprio 0
	s_barrier
	s_add_i32 s70, s70, s54
	v_lshl_add_u64 v[212:213], s[68:69], 0, v[200:201]
	s_mov_b32 m0, s70
	ds_read_b128 v[160:163], v247 offset:16384
	ds_read_b128 v[164:167], v247 offset:17408
	ds_read_b128 v[168:171], v247 offset:18432
	ds_read_b128 v[176:179], v247 offset:19456
	ds_read_b128 v[184:187], v247 offset:20480
	ds_read_b128 v[188:191], v247 offset:21504
	ds_read_b128 v[192:195], v247 offset:22528
	ds_read_b128 v[208:211], v247 offset:23552
	global_load_lds_dwordx4 v[212:213], off
	s_add_i32 m0, s70, 0x2000
	v_lshl_add_u64 v[214:215], s[68:69], 0, v[78:79]
	s_add_u32 s68, s68, s25
	s_addc_u32 s69, s69, 0
	s_add_i32 s67, s67, s54
	global_load_lds_dwordx4 v[214:215], off
	v_lshl_add_u64 v[216:217], s[68:69], 0, v[200:201]
	s_mov_b32 m0, s67
	v_lshl_add_u64 v[218:219], s[68:69], 0, v[78:79]
	global_load_lds_dwordx4 v[216:217], off
	s_add_i32 m0, s67, 0x2000
	v_lshl_add_u64 v[220:221], s[48:49], 0, v[202:203]
	global_load_lds_dwordx4 v[218:219], off
	s_mov_b32 m0, s55
	v_lshl_add_u64 v[222:223], s[48:49], 0, v[198:199]
	global_load_lds_dwordx4 v[220:221], off
	s_mov_b32 m0, s56
	s_nop 0
	global_load_lds_dwordx4 v[222:223], off
	s_waitcnt vmcnt(8)
	s_waitcnt lgkmcnt(0)
	s_barrier
; #define PG8_STAGE(bufoff, gbase, voff) do { _Pragma("unroll") for (int _i = 0; _i < 2; ++_i) \
;         __builtin_amdgcn_global_load_lds((const unsigned*)((const char*)(gbase) + (voff)[_i]), (PG8_LAS unsigned*)(lds + (bufoff) + ldsw + _i * 8192), 16, 0, 0); } while (0)
; #define PG8_LDA(dst, b, h) do { _Pragma("unroll") for (int m = 0; m < 4; ++m) _Pragma("unroll") for (int k = 0; k < 2; ++k) dst[m][k] = *(const PG8_LAS bf16x8*)(lds + PG8_SA(b, h) + aoff + m * 2048 + k * 1024); } while (0)
; #define PG8_LDB(dst, b, h) do { _Pragma("unroll") for (int n = 0; n < 2; ++n) _Pragma("unroll") for (int k = 0; k < 2; ++k) dst[n][k] = *(const PG8_LAS bf16x8*)(lds + PG8_SB(b, h) + boff + n * 2048 + k * 1024); } while (0)
; #define PG8_MMA(ai, bj, At, Bt) do { __builtin_amdgcn_s_setprio(1); _Pragma("unroll") for (int m = 0; m < 4; ++m) _Pragma("unroll") for (int n = 0; n < 2; ++n) _Pragma("unroll") for (int k = 0; k < 2; ++k) \
;         acc[ai][bj][m][n] = __builtin_amdgcn_mfma_f32_16x16x32_bf16(Bt[n][k], At[m][k], acc[ai][bj][m][n], 0, 0, 0); __builtin_amdgcn_s_setprio(0); } while (0)
; #define PG8_WAIT_V(n) asm volatile("s_waitcnt vmcnt(" #n ")" ::: "memory")
; #define PG8_WAIT_L(n) asm volatile("s_waitcnt lgkmcnt(" #n ")" ::: "memory")
; #define PG8_BAR __builtin_amdgcn_s_barrier()
; #define PG8_SCHED __builtin_amdgcn_sched_barrier(0)
; template <class Epi, class Sched, bool ALIGN_EPI = false, bool SP2 = false>
; __device__ __forceinline__ void gemm_phase(PG8_LAS unsigned char* lds, const Gemm g, const Sched& S, const Epi& E) {
;     ...
;             PG8_WAIT_V(8); PG8_WAIT_L(0); PG8_BAR; PG8_MMA(1, 0, At, B0); PG8_MMA(1, 1, At, B1); PG8_BAR; PG8_SCHED;
;             PG8_LDB(B0, 1, 0); PG8_LDB(B1, 1, 1); PG8_SCHED; PG8_LDA(At, 1, 0); PG8_STAGE(PG8_SA(0, 1), a2 + hstepA, voffA);
;             PG8_WAIT_V(8); PG8_WAIT_L(0); PG8_BAR; PG8_MMA(0, 0, At, B0); PG8_MMA(0, 1, At, B1); PG8_BAR; PG8_SCHED;
	s_setprio 1
	s_waitcnt lgkmcnt(0)
	v_mfma_f32_16x16x32_bf16 v[62:65], v[120:123], v[160:163], 0
	v_mfma_f32_16x16x32_bf16 v[58:61], v[136:139], v[160:163], 0
	v_mfma_f32_16x16x32_bf16 v[46:49], v[120:123], v[168:171], 0
	v_mfma_f32_16x16x32_bf16 v[42:45], v[136:139], v[168:171], 0
	v_mfma_f32_16x16x32_bf16 v[30:33], v[120:123], v[184:187], 0
	v_mfma_f32_16x16x32_bf16 v[26:29], v[136:139], v[184:187], 0
	v_mfma_f32_16x16x32_bf16 v[14:17], v[120:123], v[192:195], 0
	v_mfma_f32_16x16x32_bf16 v[10:13], v[136:139], v[192:195], 0
	v_mfma_f32_16x16x32_bf16 v[62:65], v[132:135], v[164:167], v[62:65]
	v_mfma_f32_16x16x32_bf16 v[58:61], v[140:143], v[164:167], v[58:61]
	v_mfma_f32_16x16x32_bf16 v[46:49], v[132:135], v[176:179], v[46:49]
	v_mfma_f32_16x16x32_bf16 v[42:45], v[140:143], v[176:179], v[42:45]
	v_mfma_f32_16x16x32_bf16 v[30:33], v[132:135], v[188:191], v[30:33]
	v_mfma_f32_16x16x32_bf16 v[26:29], v[140:143], v[188:191], v[26:29]
	v_mfma_f32_16x16x32_bf16 v[14:17], v[132:135], v[208:211], v[14:17]
	v_mfma_f32_16x16x32_bf16 v[10:13], v[140:143], v[208:211], v[10:13]
	v_mfma_f32_16x16x32_bf16 v[54:57], v[144:147], v[160:163], 0
	v_mfma_f32_16x16x32_bf16 v[50:53], v[152:155], v[160:163], 0
	v_mfma_f32_16x16x32_bf16 v[38:41], v[144:147], v[168:171], 0
	v_mfma_f32_16x16x32_bf16 v[34:37], v[152:155], v[168:171], 0
	v_mfma_f32_16x16x32_bf16 v[22:25], v[144:147], v[184:187], 0
	v_mfma_f32_16x16x32_bf16 v[18:21], v[152:155], v[184:187], 0
	v_mfma_f32_16x16x32_bf16 v[6:9], v[144:147], v[192:195], 0
	v_mfma_f32_16x16x32_bf16 v[2:5], v[152:155], v[192:195], 0
	v_mfma_f32_16x16x32_bf16 v[54:57], v[148:151], v[164:167], v[54:57]
	v_mfma_f32_16x16x32_bf16 v[50:53], v[156:159], v[164:167], v[50:53]
	v_mfma_f32_16x16x32_bf16 v[38:41], v[148:151], v[176:179], v[38:41]
	v_mfma_f32_16x16x32_bf16 v[34:37], v[156:159], v[176:179], v[34:37]
	v_mfma_f32_16x16x32_bf16 v[22:25], v[148:151], v[188:191], v[22:25]
	v_mfma_f32_16x16x32_bf16 v[18:21], v[156:159], v[188:191], v[18:21]
	v_mfma_f32_16x16x32_bf16 v[6:9], v[148:151], v[208:211], v[6:9]
	v_mfma_f32_16x16x32_bf16 v[2:5], v[156:159], v[208:211], v[2:5]
	s_setprio 0
	s_barrier
	s_add_i32 s67, 0, 0x18000
	s_add_i32 s68, 0, 0x1c000
	v_add_u32_e32 v140, s67, v243
	v_add_u32_e32 v156, s68, v243
	ds_read_b128 v[120:123], v140
	ds_read_b128 v[132:135], v140 offset:1024
	ds_read_b128 v[136:139], v140 offset:2048
	ds_read_b128 v[140:143], v140 offset:3072
	ds_read_b128 v[144:147], v156
	ds_read_b128 v[148:151], v156 offset:1024
	ds_read_b128 v[152:155], v156 offset:2048
	ds_read_b128 v[156:159], v156 offset:3072
	s_add_u32 s48, s48, s0
	s_addc_u32 s49, s49, 0
	s_mov_b32 m0, s57
	v_lshl_add_u64 v[224:225], s[48:49], 0, v[202:203]
	ds_read_b128 v[160:163], v247 offset:32768
	ds_read_b128 v[164:167], v247 offset:33792
	ds_read_b128 v[168:171], v247 offset:34816
	ds_read_b128 v[176:179], v247 offset:35840
	ds_read_b128 v[184:187], v247 offset:36864
	ds_read_b128 v[188:191], v247 offset:37888
	ds_read_b128 v[192:195], v247 offset:38912
	ds_read_b128 v[208:211], v247 offset:39936
	global_load_lds_dwordx4 v[224:225], off
	v_lshl_add_u64 v[224:225], s[48:49], 0, v[198:199]
	s_mov_b32 m0, s58
	s_nop 0
	global_load_lds_dwordx4 v[224:225], off
	s_waitcnt vmcnt(8)
	s_waitcnt lgkmcnt(0)
	s_barrier
	s_setprio 1
	s_waitcnt lgkmcnt(0)
	v_mfma_f32_16x16x32_bf16 v[180:183], v[120:123], v[160:163], v[180:183]
	v_mfma_f32_16x16x32_bf16 v[172:175], v[136:139], v[160:163], v[172:175]
	v_mfma_f32_16x16x32_bf16 v[116:119], v[120:123], v[168:171], v[116:119]
	v_mfma_f32_16x16x32_bf16 v[112:115], v[136:139], v[168:171], v[112:115]
	v_mfma_f32_16x16x32_bf16 v[100:103], v[120:123], v[184:187], v[100:103]
	v_mfma_f32_16x16x32_bf16 v[96:99], v[136:139], v[184:187], v[96:99]
	v_mfma_f32_16x16x32_bf16 v[84:87], v[120:123], v[192:195], v[84:87]
	v_mfma_f32_16x16x32_bf16 v[74:77], v[136:139], v[192:195], v[74:77]
	v_mfma_f32_16x16x32_bf16 v[180:183], v[132:135], v[164:167], v[180:183]
	v_mfma_f32_16x16x32_bf16 v[172:175], v[140:143], v[164:167], v[172:175]
	v_mfma_f32_16x16x32_bf16 v[116:119], v[132:135], v[176:179], v[116:119]
	v_mfma_f32_16x16x32_bf16 v[112:115], v[140:143], v[176:179], v[112:115]
	v_mfma_f32_16x16x32_bf16 v[100:103], v[132:135], v[188:191], v[100:103]
	v_mfma_f32_16x16x32_bf16 v[96:99], v[140:143], v[188:191], v[96:99]
	v_mfma_f32_16x16x32_bf16 v[84:87], v[132:135], v[208:211], v[84:87]
	v_mfma_f32_16x16x32_bf16 v[74:77], v[140:143], v[208:211], v[74:77]
	v_mfma_f32_16x16x32_bf16 v[128:131], v[144:147], v[160:163], v[128:131]
	v_mfma_f32_16x16x32_bf16 v[124:127], v[152:155], v[160:163], v[124:127]
	v_mfma_f32_16x16x32_bf16 v[108:111], v[144:147], v[168:171], v[108:111]
	v_mfma_f32_16x16x32_bf16 v[104:107], v[152:155], v[168:171], v[104:107]
	v_mfma_f32_16x16x32_bf16 v[92:95], v[144:147], v[184:187], v[92:95]
	v_mfma_f32_16x16x32_bf16 v[88:91], v[152:155], v[184:187], v[88:91]
	v_mfma_f32_16x16x32_bf16 v[70:73], v[144:147], v[192:195], v[70:73]
	v_mfma_f32_16x16x32_bf16 v[66:69], v[152:155], v[192:195], v[66:69]
	v_mfma_f32_16x16x32_bf16 v[128:131], v[148:151], v[164:167], v[128:131]
	v_mfma_f32_16x16x32_bf16 v[124:127], v[156:159], v[164:167], v[124:127]
	v_mfma_f32_16x16x32_bf16 v[108:111], v[148:151], v[176:179], v[108:111]
	v_mfma_f32_16x16x32_bf16 v[104:107], v[156:159], v[176:179], v[104:107]
	v_mfma_f32_16x16x32_bf16 v[92:95], v[148:151], v[188:191], v[92:95]
	v_mfma_f32_16x16x32_bf16 v[88:91], v[156:159], v[188:191], v[88:91]
	v_mfma_f32_16x16x32_bf16 v[70:73], v[148:151], v[208:211], v[70:73]
	v_mfma_f32_16x16x32_bf16 v[66:69], v[156:159], v[208:211], v[66:69]
	s_setprio 0
	s_barrier
; #define PG8_STAGE(bufoff, gbase, voff) do { _Pragma("unroll") for (int _i = 0; _i < 2; ++_i) \
;         __builtin_amdgcn_global_load_lds((const unsigned*)((const char*)(gbase) + (voff)[_i]), (PG8_LAS unsigned*)(lds + (bufoff) + ldsw + _i * 8192), 16, 0, 0); } while (0)
; #define PG8_LDA(dst, b, h) do { _Pragma("unroll") for (int m = 0; m < 4; ++m) _Pragma("unroll") for (int k = 0; k < 2; ++k) dst[m][k] = *(const PG8_LAS bf16x8*)(lds + PG8_SA(b, h) + aoff + m * 2048 + k * 1024); } while (0)
; #define PG8_MMA(ai, bj, At, Bt) do { __builtin_amdgcn_s_setprio(1); _Pragma("unroll") for (int m = 0; m < 4; ++m) _Pragma("unroll") for (int n = 0; n < 2; ++n) _Pragma("unroll") for (int k = 0; k < 2; ++k) \
;         acc[ai][bj][m][n] = __builtin_amdgcn_mfma_f32_16x16x32_bf16(Bt[n][k], At[m][k], acc[ai][bj][m][n], 0, 0, 0); __builtin_amdgcn_s_setprio(0); } while (0)
; #define PG8_WAIT_V(n) asm volatile("s_waitcnt vmcnt(" #n ")" ::: "memory")
; #define PG8_WAIT_L(n) asm volatile("s_waitcnt lgkmcnt(" #n ")" ::: "memory")
; #define PG8_BAR __builtin_amdgcn_s_barrier()
; #define PG8_SCHED __builtin_amdgcn_sched_barrier(0)
; template <class Epi, class Sched, bool ALIGN_EPI = false, bool SP2 = false>
; __device__ __forceinline__ void gemm_phase(PG8_LAS unsigned char* lds, const Gemm g, const Sched& S, const Epi& E) {
;     ...
;         for (int t = 0; t < nt; t += 2) {
;     ...
;             PG8_LDA(At, 1, 1); PG8_STAGE(PG8_SB(1, 0), b3, voffB); PG8_STAGE(PG8_SB(1, 1), b3 + hstep, voffB); PG8_STAGE(PG8_SA(1, 0), a3, voffA);
;             PG8_WAIT_V(8); PG8_WAIT_L(0); PG8_BAR; PG8_MMA(1, 0, At, B0); PG8_MMA(1, 1, At, B1); PG8_BAR; PG8_SCHED;
	s_add_i32 s48, s67, s54
	v_lshl_add_u64 v[212:213], v[212:213], 0, s[26:27]
	s_mov_b32 m0, s48
	ds_read_b128 v[160:163], v247 offset:49152
	ds_read_b128 v[164:167], v247 offset:50176
	ds_read_b128 v[168:171], v247 offset:51200
	ds_read_b128 v[176:179], v247 offset:52224
	ds_read_b128 v[184:187], v247 offset:53248
	ds_read_b128 v[188:191], v247 offset:54272
	ds_read_b128 v[192:195], v247 offset:55296
	ds_read_b128 v[208:211], v247 offset:56320
	global_load_lds_dwordx4 v[212:213], off
	v_lshl_add_u64 v[212:213], v[214:215], 0, s[26:27]
	s_add_i32 m0, s48, 0x2000
	s_add_i32 s48, s68, s54
	global_load_lds_dwordx4 v[212:213], off
	v_lshl_add_u64 v[212:213], v[216:217], 0, s[26:27]
	s_mov_b32 m0, s48
	s_nop 0
	global_load_lds_dwordx4 v[212:213], off
	v_lshl_add_u64 v[212:213], v[218:219], 0, s[26:27]
	s_add_i32 m0, s48, 0x2000
	s_nop 0
	global_load_lds_dwordx4 v[212:213], off
	v_lshl_add_u64 v[212:213], v[220:221], 0, s[26:27]
	s_mov_b32 m0, s59
	s_nop 0
	global_load_lds_dwordx4 v[212:213], off
	v_lshl_add_u64 v[212:213], v[222:223], 0, s[26:27]
	s_mov_b32 m0, s60
	s_nop 0
	global_load_lds_dwordx4 v[212:213], off
	s_waitcnt vmcnt(8)
	s_waitcnt lgkmcnt(0)
	s_barrier
	s_setprio 1
	s_waitcnt lgkmcnt(0)
	v_mfma_f32_16x16x32_bf16 v[62:65], v[120:123], v[160:163], v[62:65]
	v_mfma_f32_16x16x32_bf16 v[58:61], v[136:139], v[160:163], v[58:61]
	v_mfma_f32_16x16x32_bf16 v[46:49], v[120:123], v[168:171], v[46:49]
	v_mfma_f32_16x16x32_bf16 v[42:45], v[136:139], v[168:171], v[42:45]
	v_mfma_f32_16x16x32_bf16 v[30:33], v[120:123], v[184:187], v[30:33]
	v_mfma_f32_16x16x32_bf16 v[26:29], v[136:139], v[184:187], v[26:29]
	v_mfma_f32_16x16x32_bf16 v[14:17], v[120:123], v[192:195], v[14:17]
	v_mfma_f32_16x16x32_bf16 v[10:13], v[136:139], v[192:195], v[10:13]
	v_mfma_f32_16x16x32_bf16 v[62:65], v[132:135], v[164:167], v[62:65]
	v_mfma_f32_16x16x32_bf16 v[58:61], v[140:143], v[164:167], v[58:61]
	v_mfma_f32_16x16x32_bf16 v[46:49], v[132:135], v[176:179], v[46:49]
	v_mfma_f32_16x16x32_bf16 v[42:45], v[140:143], v[176:179], v[42:45]
	v_mfma_f32_16x16x32_bf16 v[30:33], v[132:135], v[188:191], v[30:33]
	v_mfma_f32_16x16x32_bf16 v[26:29], v[140:143], v[188:191], v[26:29]
	v_mfma_f32_16x16x32_bf16 v[14:17], v[132:135], v[208:211], v[14:17]
	v_mfma_f32_16x16x32_bf16 v[10:13], v[140:143], v[208:211], v[10:13]
	v_mfma_f32_16x16x32_bf16 v[54:57], v[144:147], v[160:163], v[54:57]
	v_mfma_f32_16x16x32_bf16 v[50:53], v[152:155], v[160:163], v[50:53]
	v_mfma_f32_16x16x32_bf16 v[38:41], v[144:147], v[168:171], v[38:41]
	v_mfma_f32_16x16x32_bf16 v[34:37], v[152:155], v[168:171], v[34:37]
	v_mfma_f32_16x16x32_bf16 v[22:25], v[144:147], v[184:187], v[22:25]
	v_mfma_f32_16x16x32_bf16 v[18:21], v[152:155], v[184:187], v[18:21]
	v_mfma_f32_16x16x32_bf16 v[6:9], v[144:147], v[192:195], v[6:9]
	v_mfma_f32_16x16x32_bf16 v[2:5], v[152:155], v[192:195], v[2:5]
	v_mfma_f32_16x16x32_bf16 v[54:57], v[148:151], v[164:167], v[54:57]
	v_mfma_f32_16x16x32_bf16 v[50:53], v[156:159], v[164:167], v[50:53]
	v_mfma_f32_16x16x32_bf16 v[38:41], v[148:151], v[176:179], v[38:41]
	v_mfma_f32_16x16x32_bf16 v[34:37], v[156:159], v[176:179], v[34:37]
	v_mfma_f32_16x16x32_bf16 v[22:25], v[148:151], v[188:191], v[22:25]
	v_mfma_f32_16x16x32_bf16 v[18:21], v[156:159], v[188:191], v[18:21]
	v_mfma_f32_16x16x32_bf16 v[6:9], v[148:151], v[208:211], v[6:9]
	v_mfma_f32_16x16x32_bf16 v[2:5], v[156:159], v[208:211], v[2:5]
	s_setprio 0
	s_barrier
	s_add_u32 s46, s46, 0x100
	s_addc_u32 s47, s47, 0
	s_add_u32 s5, s5, 0x100
	s_addc_u32 s19, s19, 0
	s_cmp_ge_u32 s66, s61
	s_mov_b32 s48, s66
